# first in-proj instance: q and K epilogue paths use permlane16_swap + dwordx4 stores (2 per row instead of 4)
# baseline (speedup 1.0000x reference)
; template <int EPI>
; __device__ __forceinline__ void gemm_epilogue(const f32x4 (&acc)[2][2][4][2], const Unit& u, int wr, int wc, int fr, int fq,
;                                               const EpiArgs& ea, const float (&rs_pre)[2][4]) {
;     ...
;   } else if constexpr (EPI == EPI_EVEN || EPI == EPI_ODD) {
;     const int unit = u.pn * 4 + wc;
;     constexpr int LD = (EPI == EPI_EVEN) ? 1536 : 1280;
;     const int qlo = (EPI == EPI_EVEN) ? 16 : 0, qhi = (EPI == EPI_EVEN) ? 24 : 8, khi = (EPI == EPI_EVEN) ? 32 : 10;
;     const bool plain = (EPI == EPI_EVEN) ? (unit < 16) : (unit >= 12);
;     if (plain) {
; #pragma unroll
;       for (int ai = 0; ai < 2; ++ai)
; #pragma unroll
;         for (int m = 0; m < 4; ++m) {
;           const int row = row0 + ai * 128 + m * 16;
;           const float rs = rsr[ai][m];
; #pragma unroll
;           for (int bj = 0; bj < 2; ++bj)
; #pragma unroll
;             for (int n = 0; n < 2; ++n)
;               *reinterpret_cast<uint2*>(ea.out_bf + (size_t)row * LD + lc0 + bj * 32 + n * 16) = pack4(acc[ai][bj][m][n] * rs);
;         }
;     } else if (unit >= qlo && unit < khi) {
;       const bool isq = unit < qhi;
;       const float* gn = isq ? ea.aux_f0 : ea.aux_f1;
;       const float sc = isq ? QSCALE : 1.f;
;       f32x4 gv[2][2];
; #pragma unroll
;       for (int bj = 0; bj < 2; ++bj)
; #pragma unroll
;         for (int n = 0; n < 2; ++n) gv[bj][n] = *reinterpret_cast<const f32x4*>(gn + bj * 32 + n * 16 + 4 * fq) * sc;
.LBB0_583:
	s_lshl_b32 s14, s14, 8
	v_readlane_b32 s0, v251, 36
	s_add_i32 s14, s14, s0
	v_or_b32_e32 v172, s14, v113
	v_readlane_b32 s0, v255, 14
	v_ashrrev_i32_e32 v173, 31, v172
	v_readlane_b32 s1, v255, 15
	v_or_b32_e32 v168, 16, v172
	v_ashrrev_i32_e32 v169, 31, v168
	v_lshl_add_u64 v[130:131], v[172:173], 2, s[0:1]
	global_load_dword v134, v[130:131], off
	global_load_dword v137, v[130:131], off offset:576
	global_load_dword v154, v[130:131], off offset:640
	v_lshl_add_u64 v[132:133], v[168:169], 2, s[0:1]
	global_load_dword v135, v[132:133], off
	v_or_b32_e32 v164, 32, v172
	v_ashrrev_i32_e32 v165, 31, v164
	v_lshl_add_u64 v[132:133], v[164:165], 2, s[0:1]
	global_load_dword v136, v[132:133], off
	v_or_b32_e32 v160, 48, v172
	v_ashrrev_i32_e32 v161, 31, v160
	v_lshl_add_u64 v[132:133], v[160:161], 2, s[0:1]
	global_load_dword v132, v[132:133], off
	s_lshl_b32 s0, s2, 2
	global_load_dword v133, v[130:131], off offset:512
	v_readlane_b32 s1, v251, 48
	global_load_dword v130, v[130:131], off offset:704
	s_or_b32 s76, s0, s1
	v_add_u32_e32 v167, 0x80, v172
	v_add_u32_e32 v165, 0x90, v172
	v_add_u32_e32 v163, 0xa0, v172
	v_add_u32_e32 v161, 0xb0, v172
	v_lshl_add_u32 v178, s2, 8, v157
	s_mov_b64 s[0:1], -1
	s_cmp_lt_i32 s76, 12
	s_waitcnt vmcnt(0)
	v_fmamk_f32 v131, v134, 0x3a800000, v218
	v_cmp_gt_f32_e32 vcc, s26, v131
	v_mul_f32_e32 v134, 0x4b800000, v131
	v_fmamk_f32 v130, v130, 0x3a800000, v218
	v_cndmask_b32_e32 v131, v131, v134, vcc
	v_rsq_f32_e32 v131, v131
	s_nop 0
	v_mul_f32_e32 v134, 0x45800000, v131
	v_cndmask_b32_e32 v176, v131, v134, vcc
	v_fmamk_f32 v131, v135, 0x3a800000, v218
	v_cmp_gt_f32_e32 vcc, s26, v131
	v_mul_f32_e32 v134, 0x4b800000, v131
	s_nop 0
	v_cndmask_b32_e32 v131, v131, v134, vcc
	v_rsq_f32_e32 v131, v131
	s_nop 0
	v_mul_f32_e32 v134, 0x45800000, v131
	v_cndmask_b32_e32 v174, v131, v134, vcc
	v_fmamk_f32 v131, v136, 0x3a800000, v218
	v_cmp_gt_f32_e32 vcc, s26, v131
	v_mul_f32_e32 v134, 0x4b800000, v131
	s_nop 0
	v_cndmask_b32_e32 v131, v131, v134, vcc
	v_rsq_f32_e32 v131, v131
	s_nop 0
	v_mul_f32_e32 v134, 0x45800000, v131
	v_cndmask_b32_e32 v170, v131, v134, vcc
	v_fmamk_f32 v131, v132, 0x3a800000, v218
	v_cmp_gt_f32_e32 vcc, s26, v131
	v_mul_f32_e32 v132, 0x4b800000, v131
	s_nop 0
	v_cndmask_b32_e32 v131, v131, v132, vcc
	v_rsq_f32_e32 v131, v131
	s_nop 0
	v_mul_f32_e32 v132, 0x45800000, v131
	v_cndmask_b32_e32 v166, v131, v132, vcc
	v_fmamk_f32 v131, v133, 0x3a800000, v218
	v_cmp_gt_f32_e32 vcc, s26, v131
	v_mul_f32_e32 v132, 0x4b800000, v131
	s_nop 0
	v_cndmask_b32_e32 v131, v131, v132, vcc
	v_rsq_f32_e32 v131, v131
	s_nop 0
	v_mul_f32_e32 v132, 0x45800000, v131
	v_cndmask_b32_e32 v162, v131, v132, vcc
	v_fmamk_f32 v131, v137, 0x3a800000, v218
	v_cmp_gt_f32_e32 vcc, s26, v131
	v_mul_f32_e32 v132, 0x4b800000, v131
	s_nop 0
	v_cndmask_b32_e32 v131, v131, v132, vcc
	v_rsq_f32_e32 v131, v131
	s_nop 0
	v_mul_f32_e32 v132, 0x45800000, v131
	v_cndmask_b32_e32 v158, v131, v132, vcc
	v_fmamk_f32 v131, v154, 0x3a800000, v218
	v_cmp_gt_f32_e32 vcc, s26, v131
	v_mul_f32_e32 v132, 0x4b800000, v131
	s_nop 0
	v_cndmask_b32_e32 v131, v131, v132, vcc
	v_rsq_f32_e32 v131, v131
	s_nop 0
	v_mul_f32_e32 v132, 0x45800000, v131
	v_cndmask_b32_e32 v156, v131, v132, vcc
	v_cmp_gt_f32_e32 vcc, s26, v130
	v_mul_f32_e32 v131, 0x4b800000, v130
	s_nop 0
	v_cndmask_b32_e32 v130, v130, v131, vcc
	v_rsq_f32_e32 v130, v130
	s_nop 0
	v_mul_f32_e32 v131, 0x45800000, v130
	v_cndmask_b32_e32 v154, v130, v131, vcc
	s_cbranch_scc0 .LBB0_618
	s_cmp_lt_i32 s2, 0
	s_cselect_b64 s[0:1], -1, 0
	s_cmp_gt_i32 s76, 9
	s_cselect_b64 s[22:23], -1, 0
	s_or_b64 s[0:1], s[0:1], s[22:23]
	s_and_b64 vcc, exec, s[0:1]
	s_cbranch_vccnz .LBB0_617
	s_cmp_gt_i32 s76, 7
	s_cselect_b64 s[16:17], -1, 0
	s_cmp_lt_i32 s76, 8
	s_cselect_b64 vcc, -1, 0
	s_and_b64 s[0:1], vcc, exec
	v_readlane_b32 s52, v250, 34
	v_readlane_b32 s0, v255, 36
	v_readlane_b32 s60, v250, 42
	v_readlane_b32 s61, v250, 43
	v_readlane_b32 s62, v250, 44
	v_readlane_b32 s63, v250, 45
	v_readlane_b32 s1, v255, 37
	s_cselect_b32 s2, s61, s63
	s_cselect_b32 s15, s60, s62
	s_lshl_b64 s[0:1], s[0:1], 2
	s_add_u32 s0, s15, s0
	s_addc_u32 s1, s2, s1
	v_lshl_add_u64 v[136:137], v[142:143], 2, s[0:1]
	global_load_dwordx4 v[130:133], v[136:137], off
	v_cndmask_b32_e32 v134, 1.0, v223, vcc
	v_pk_mul_f32 v[200:201], v[122:123], v[176:177] op_sel_hi:[1,0]
	v_pk_mul_f32 v[206:207], v[118:119], v[176:177] op_sel_hi:[1,0]
	v_pk_mul_f32 v[202:203], v[120:121], v[176:177] op_sel_hi:[1,0]
	v_pk_mul_f32 v[210:211], v[114:115], v[176:177] op_sel_hi:[1,0]
	v_pk_mul_f32 v[208:209], v[116:117], v[176:177] op_sel_hi:[1,0]
	v_and_b32_e32 v179, 0xfcf, v172
	s_add_i32 s76, s76, -8
	s_ashr_i32 s2, s14, 12
	s_mov_b64 s[0:1], -1
	v_readlane_b32 s53, v250, 35
	v_readlane_b32 s54, v250, 36
	v_readlane_b32 s55, v250, 37
	v_readlane_b32 s56, v250, 38
	v_readlane_b32 s57, v250, 39
	v_readlane_b32 s58, v250, 40
	v_readlane_b32 s59, v250, 41
	v_readlane_b32 s64, v250, 46
	v_readlane_b32 s65, v250, 47
	v_readlane_b32 s66, v250, 48
	v_readlane_b32 s67, v250, 49
	s_waitcnt vmcnt(0)
	v_pk_mul_f32 v[180:181], v[134:135], v[132:133] op_sel_hi:[0,1]
	v_pk_mul_f32 v[186:187], v[134:135], v[130:131] op_sel_hi:[0,1]
	global_load_dwordx4 v[130:133], v[136:137], off offset:64
	s_waitcnt vmcnt(0)
	v_pk_mul_f32 v[188:189], v[134:135], v[132:133] op_sel_hi:[0,1]
	v_pk_mul_f32 v[190:191], v[134:135], v[130:131] op_sel_hi:[0,1]
	global_load_dwordx4 v[130:133], v[136:137], off offset:128
	s_waitcnt vmcnt(0)
	v_pk_mul_f32 v[192:193], v[134:135], v[132:133] op_sel_hi:[0,1]
	v_pk_mul_f32 v[194:195], v[134:135], v[130:131] op_sel_hi:[0,1]
	global_load_dwordx4 v[130:133], v[136:137], off offset:192
	v_pk_mul_f32 v[136:137], v[124:125], v[176:177] op_sel_hi:[1,0]
	s_waitcnt vmcnt(0)
; template <int EPI>
; __device__ __forceinline__ void gemm_epilogue(const f32x4 (&acc)[2][2][4][2], const Unit& u, int wr, int wc, int fr, int fq,
;                                               const EpiArgs& ea, const float (&rs_pre)[2][4]) {
;     ...
;       for (int ai = 0; ai < 2; ++ai)
; #pragma unroll
;         for (int m = 0; m < 4; ++m) {
;           const int row = row0 + ai * 128 + m * 16;
;           const float rs = rsr[ai][m];
;           f32x4 v[2][2];
;           float sq = 0.f;
; #pragma unroll
;           for (int bj = 0; bj < 2; ++bj)
; #pragma unroll
;             for (int n = 0; n < 2; ++n) {
;               v[bj][n] = acc[ai][bj][m][n] * rs;
;               sq += v[bj][n][0] * v[bj][n][0] + v[bj][n][1] * v[bj][n][1] + v[bj][n][2] * v[bj][n][2] + v[bj][n][3] * v[bj][n][3];
;             }
;           sq = xsum32(xsum16(sq));
;           const float hr = rsqrtf(sq * (1.f / 64.f) + EPS);
; #pragma unroll
;           for (int bj = 0; bj < 2; ++bj)
; #pragma unroll
;             for (int n = 0; n < 2; ++n) v[bj][n] = v[bj][n] * hr * gv[bj][n];
;           if constexpr (EPI == EPI_ODD) {
;             const int pos = row & 4095;
;             const float2* rope = reinterpret_cast<const float2*>(ea.aux_f2) + pos * 32 + 4 * fq;
; #pragma unroll
;             for (int n = 0; n < 2; ++n) {
;               f32x4 c01 = *reinterpret_cast<const f32x4*>(rope + n * 16);
;               f32x4 c23 = *reinterpret_cast<const f32x4*>(rope + n * 16 + 2);
;               float cs[4] = {c01[0], c01[2], c23[0], c23[2]}, sn[4] = {c01[1], c01[3], c23[1], c23[3]};
;               f32x4 x1 = v[0][n], x2 = v[1][n];
; #pragma unroll
;               for (int i = 0; i < 4; ++i) {
;                 v[0][n][i] = x1[i] * cs[i] - x2[i] * sn[i];
;                 v[1][n][i] = x2[i] * cs[i] + x1[i] * sn[i];
;               }
;             }
;           }
;           if (isq) {
; #pragma unroll
;             for (int bj = 0; bj < 2; ++bj)
; #pragma unroll
;               for (int n = 0; n < 2; ++n)
;                 *reinterpret_cast<uint2*>(ea.out_bf + (size_t)row * LD + lc0 + bj * 32 + n * 16) = pack4(v[bj][n]);
;           } else {
;             const int kh = unit - qhi, b = row >> 12, t = row & 4095;
;             u16* kb = ea.kp + ((size_t)((b * ea.nh + kh) * 128 + (t >> 5)) * 4) * 512 + ((fq >> 1) * 32 + (t & 31)) * 8 + (fq & 1) * 4;
; #pragma unroll
	v_pk_mul_f32 v[196:197], v[134:135], v[132:133] op_sel_hi:[0,1]
	v_pk_mul_f32 v[132:133], v[126:127], v[176:177] op_sel_hi:[1,0]
	v_pk_mul_f32 v[198:199], v[134:135], v[130:131] op_sel_hi:[0,1]
	v_mul_f32_e32 v134, v133, v133
	v_mul_f32_e32 v135, v201, v201
	v_pk_mul_f32 v[130:131], v[128:129], v[176:177] op_sel_hi:[1,0]
	v_fmac_f32_e32 v134, v132, v132
	v_fmac_f32_e32 v135, v200, v200
	v_fmac_f32_e32 v134, v130, v130
	v_fmac_f32_e32 v135, v136, v136
	v_fmac_f32_e32 v134, v131, v131
	v_fmac_f32_e32 v135, v137, v137
	v_add_f32_e32 v134, v134, v135
	v_mul_f32_e32 v135, v207, v207
	v_fmac_f32_e32 v135, v206, v206
	v_fmac_f32_e32 v135, v202, v202
	v_fmac_f32_e32 v135, v203, v203
	v_add_f32_e32 v134, v135, v134
	v_mul_f32_e32 v135, v211, v211
	v_fmac_f32_e32 v135, v210, v210
	v_fmac_f32_e32 v135, v208, v208
	v_fmac_f32_e32 v135, v209, v209
	v_add_f32_e32 v134, v135, v134
	v_mov_b32_e32 v135, v134
	s_nop 1
	v_permlane16_swap_b32_e32 v134, v135
	v_add_f32_e32 v134, v134, v135
	v_mov_b32_e32 v135, v134
	s_nop 1
	v_permlane32_swap_b32_e32 v134, v135
	v_add_f32_e32 v134, v134, v135
	v_fmamk_f32 v134, v134, 0x3c800000, v218
	v_cmp_gt_f32_e32 vcc, s26, v134
	v_mul_f32_e32 v135, 0x4b800000, v134
	s_nop 0
	v_cndmask_b32_e32 v134, v134, v135, vcc
	v_rsq_f32_e32 v134, v134
	s_nop 0
	v_mul_f32_e32 v135, 0x45800000, v134
	v_cndmask_b32_e32 v182, v134, v135, vcc
	v_pk_mul_f32 v[132:133], v[132:133], v[182:183] op_sel_hi:[1,0]
	v_pk_mul_f32 v[136:137], v[136:137], v[182:183] op_sel_hi:[1,0]
	v_pk_mul_f32 v[134:135], v[186:187], v[132:133]
	v_pk_mul_f32 v[132:133], v[200:201], v[182:183] op_sel_hi:[1,0]
	v_pk_mul_f32 v[200:201], v[188:189], v[136:137]
	v_pk_mul_f32 v[204:205], v[190:191], v[132:133]
	v_pk_mul_f32 v[132:133], v[202:203], v[182:183] op_sel_hi:[1,0]
	v_pk_mul_f32 v[202:203], v[208:209], v[182:183] op_sel_hi:[1,0]
	v_lshlrev_b32_e32 v208, 8, v179
	v_mov_b32_e32 v209, v112
	v_lshl_add_u64 v[216:217], v[144:145], 0, v[208:209]
	v_pk_mul_f32 v[136:137], v[206:207], v[182:183] op_sel_hi:[1,0]
	v_pk_mul_f32 v[206:207], v[210:211], v[182:183] op_sel_hi:[1,0]
	global_load_dwordx4 v[208:211], v[216:217], off offset:16
	global_load_dwordx4 v[212:215], v[216:217], off
	v_pk_mul_f32 v[136:137], v[194:195], v[136:137]
	v_pk_mul_f32 v[130:131], v[130:131], v[182:183] op_sel_hi:[1,0]
	v_pk_mul_f32 v[132:133], v[192:193], v[132:133]
	v_pk_mul_f32 v[130:131], v[180:181], v[130:131]
	v_pk_mul_f32 v[206:207], v[198:199], v[206:207]
	v_pk_mul_f32 v[202:203], v[196:197], v[202:203]
	s_and_b64 vcc, exec, s[16:17]
	s_waitcnt vmcnt(0)
	v_mul_f32_e32 v173, v209, v130
	v_mul_f32_e32 v169, v213, v136
	v_fma_f32 v177, v212, v134, -v169
	v_mul_f32_e32 v169, v213, v134
	v_mul_f32_e32 v134, v215, v137
	v_fma_f32 v182, v214, v135, -v134
	v_mul_f32_e32 v134, v209, v132
	v_mul_f32_e32 v171, v215, v135
	v_fma_f32 v185, v208, v130, -v134
	v_mul_f32_e32 v130, v211, v133
	v_mul_f32_e32 v175, v211, v131
	v_fmac_f32_e32 v169, v212, v136
	v_fmac_f32_e32 v171, v214, v137
	v_fmac_f32_e32 v173, v208, v132
	v_fma_f32 v208, v210, v131, -v130
	v_fmac_f32_e32 v175, v210, v133
	global_load_dwordx4 v[130:133], v[216:217], off offset:144
	global_load_dwordx4 v[134:137], v[216:217], off offset:128
	s_waitcnt vmcnt(0)
	v_mul_f32_e32 v209, v135, v206
	v_mul_f32_e32 v135, v135, v204
	v_fma_f32 v209, v134, v204, -v209
	v_fmac_f32_e32 v135, v134, v206
	v_mul_f32_e32 v134, v137, v207
	v_fma_f32 v204, v136, v205, -v134
	v_mul_f32_e32 v134, v137, v205
	v_fmac_f32_e32 v134, v136, v207
	v_mul_f32_e32 v136, v131, v202
	v_mul_f32_e32 v131, v131, v200
	v_fma_f32 v136, v130, v200, -v136
	v_fmac_f32_e32 v131, v130, v202
	v_mul_f32_e32 v130, v133, v203
	v_fma_f32 v137, v132, v201, -v130
	v_mul_f32_e32 v130, v133, v201
	v_fmac_f32_e32 v130, v132, v203
	s_cbranch_vccz .LBB0_587
	s_lshl_b32 s0, s2, 8
	s_lshl_b32 s1, s76, 7
	s_add_i32 s0, s0, s1
	v_lshrrev_b32_e32 v132, 5, v179
	v_or_b32_e32 v132, s0, v132
	v_ashrrev_i32_e32 v133, 31, v132
	v_lshlrev_b64 v[132:133], 12, v[132:133]
	v_lshl_add_u64 v[132:133], v[146:147], 0, v[132:133]
	v_cvt_pk_bf16_f32 v114, v177, v182
	v_cvt_pk_bf16_f32 v115, v185, v208
	v_cvt_pk_bf16_f32 v116, v209, v204
	v_cvt_pk_bf16_f32 v117, v136, v137
	v_cvt_pk_bf16_f32 v118, v169, v171
	v_cvt_pk_bf16_f32 v119, v173, v175
	v_cvt_pk_bf16_f32 v120, v135, v134
	v_cvt_pk_bf16_f32 v121, v131, v130
	v_mbcnt_lo_u32_b32 v122, -1, 0
	v_mbcnt_hi_u32_b32 v122, -1, v122
	v_and_b32_e32 v122, 16, v122
	v_mul_u32_u24_e32 v123, 63, v122
	v_lshrrev_b32_e32 v122, 1, v122
	v_add_u32_e32 v122, v122, v123
	v_mov_b32_e32 v123, 0
	v_permlane16_swap_b32_e32 v114, v116
	v_permlane16_swap_b32_e32 v115, v117
	v_permlane16_swap_b32_e32 v118, v120
	v_permlane16_swap_b32_e32 v119, v121
	v_lshl_add_u64 v[132:133], v[132:133], 0, v[122:123]
	global_store_dwordx4 v[132:133], v[114:117], off
	global_store_dwordx4 v[132:133], v[118:121], off offset:2048
	s_mov_b64 s[0:1], 0
.LBB0_587:
	s_andn2_b64 vcc, exec, s[0:1]
	v_ashrrev_i32_e32 v179, 31, v178
	s_cbranch_vccnz .LBB0_589
	v_mov_b64_e32 v[200:201], s[42:43]
	v_mad_i64_i32 v[200:201], s[0:1], v172, s45, v[200:201]
	v_lshl_add_u64 v[200:201], v[178:179], 1, v[200:201]
	v_cvt_pk_bf16_f32 v114, v177, v182
	v_cvt_pk_bf16_f32 v115, v185, v208
	v_cvt_pk_bf16_f32 v116, v209, v204
	v_cvt_pk_bf16_f32 v117, v136, v137
	v_cvt_pk_bf16_f32 v118, v169, v171
	v_cvt_pk_bf16_f32 v119, v173, v175
	v_cvt_pk_bf16_f32 v120, v135, v134
	v_cvt_pk_bf16_f32 v121, v131, v130
	v_mbcnt_lo_u32_b32 v122, -1, 0
	v_mbcnt_hi_u32_b32 v122, -1, v122
	v_and_b32_e32 v122, 16, v122
	v_lshrrev_b32_e32 v123, 1, v122
	v_add_u32_e32 v122, v122, v123
	v_mov_b32_e32 v123, 0
	v_permlane16_swap_b32_e32 v114, v116
	v_permlane16_swap_b32_e32 v115, v117
	v_permlane16_swap_b32_e32 v118, v120
	v_permlane16_swap_b32_e32 v119, v121
	v_lshl_add_u64 v[200:201], v[200:201], 0, v[122:123]
	global_store_dwordx4 v[200:201], v[114:117], off
	global_store_dwordx4 v[200:201], v[118:121], off offset:64
; template <int EPI>
; __device__ __forceinline__ void gemm_epilogue(const f32x4 (&acc)[2][2][4][2], const Unit& u, int wr, int wc, int fr, int fq,
;                                               const EpiArgs& ea, const float (&rs_pre)[2][4]) {
;     ...
;       for (int ai = 0; ai < 2; ++ai)
; #pragma unroll
;         for (int m = 0; m < 4; ++m) {
;           const int row = row0 + ai * 128 + m * 16;
;           const float rs = rsr[ai][m];
;           f32x4 v[2][2];
;           float sq = 0.f;
; #pragma unroll
;           for (int bj = 0; bj < 2; ++bj)
; #pragma unroll
;             for (int n = 0; n < 2; ++n) {
;               v[bj][n] = acc[ai][bj][m][n] * rs;
;               sq += v[bj][n][0] * v[bj][n][0] + v[bj][n][1] * v[bj][n][1] + v[bj][n][2] * v[bj][n][2] + v[bj][n][3] * v[bj][n][3];
;             }
;           sq = xsum32(xsum16(sq));
;           const float hr = rsqrtf(sq * (1.f / 64.f) + EPS);
; #pragma unroll
;           for (int bj = 0; bj < 2; ++bj)
; #pragma unroll
;             for (int n = 0; n < 2; ++n) v[bj][n] = v[bj][n] * hr * gv[bj][n];
;           if constexpr (EPI == EPI_ODD) {
;             const int pos = row & 4095;
;             const float2* rope = reinterpret_cast<const float2*>(ea.aux_f2) + pos * 32 + 4 * fq;
; #pragma unroll
;             for (int n = 0; n < 2; ++n) {
;               f32x4 c01 = *reinterpret_cast<const f32x4*>(rope + n * 16);
;               f32x4 c23 = *reinterpret_cast<const f32x4*>(rope + n * 16 + 2);
;               float cs[4] = {c01[0], c01[2], c23[0], c23[2]}, sn[4] = {c01[1], c01[3], c23[1], c23[3]};
;               f32x4 x1 = v[0][n], x2 = v[1][n];
; #pragma unroll
;               for (int i = 0; i < 4; ++i) {
;                 v[0][n][i] = x1[i] * cs[i] - x2[i] * sn[i];
;                 v[1][n][i] = x2[i] * cs[i] + x1[i] * sn[i];
;               }
;             }
;           }
;           if (isq) {
; #pragma unroll
;             for (int bj = 0; bj < 2; ++bj)
; #pragma unroll
;               for (int n = 0; n < 2; ++n)
;                 *reinterpret_cast<uint2*>(ea.out_bf + (size_t)row * LD + lc0 + bj * 32 + n * 16) = pack4(v[bj][n]);
;           } else {
;             const int kh = unit - qhi, b = row >> 12, t = row & 4095;
;             u16* kb = ea.kp + ((size_t)((b * ea.nh + kh) * 128 + (t >> 5)) * 4) * 512 + ((fq >> 1) * 32 + (t & 31)) * 8 + (fq & 1) * 4;
; #pragma unroll
.LBB0_589:
	v_pk_mul_f32 v[132:133], v[108:109], v[174:175] op_sel_hi:[1,0]
	v_pk_mul_f32 v[200:201], v[104:105], v[174:175] op_sel_hi:[1,0]
	v_mul_f32_e32 v134, v133, v133
	v_mul_f32_e32 v135, v201, v201
	v_pk_mul_f32 v[130:131], v[110:111], v[174:175] op_sel_hi:[1,0]
	v_fmac_f32_e32 v134, v132, v132
	v_pk_mul_f32 v[136:137], v[106:107], v[174:175] op_sel_hi:[1,0]
	v_fmac_f32_e32 v135, v200, v200
	v_fmac_f32_e32 v134, v130, v130
	v_fmac_f32_e32 v135, v136, v136
	v_fmac_f32_e32 v134, v131, v131
	v_fmac_f32_e32 v135, v137, v137
	v_pk_mul_f32 v[206:207], v[100:101], v[174:175] op_sel_hi:[1,0]
	v_add_f32_e32 v134, v134, v135
	v_mul_f32_e32 v135, v207, v207
	v_pk_mul_f32 v[202:203], v[102:103], v[174:175] op_sel_hi:[1,0]
	v_fmac_f32_e32 v135, v206, v206
	v_fmac_f32_e32 v135, v202, v202
	v_fmac_f32_e32 v135, v203, v203
	v_pk_mul_f32 v[210:211], v[96:97], v[174:175] op_sel_hi:[1,0]
	v_add_f32_e32 v134, v135, v134
	v_mul_f32_e32 v135, v211, v211
	v_pk_mul_f32 v[208:209], v[98:99], v[174:175] op_sel_hi:[1,0]
	v_fmac_f32_e32 v135, v210, v210
	v_fmac_f32_e32 v135, v208, v208
	v_fmac_f32_e32 v135, v209, v209
	v_add_f32_e32 v134, v135, v134
	v_mov_b32_e32 v135, v134
	s_nop 1
	v_permlane16_swap_b32_e32 v134, v135
	v_add_f32_e32 v134, v134, v135
	v_mov_b32_e32 v135, v134
	s_nop 1
	v_permlane32_swap_b32_e32 v134, v135
	v_add_f32_e32 v134, v134, v135
	v_fmamk_f32 v134, v134, 0x3c800000, v218
	v_cmp_gt_f32_e32 vcc, s26, v134
	v_mul_f32_e32 v135, 0x4b800000, v134
	v_readlane_b32 s58, v253, 9
	v_cndmask_b32_e32 v134, v134, v135, vcc
	v_rsq_f32_e32 v134, v134
	s_mov_b64 s[36:37], -1
	v_readlane_b32 s59, v253, 10
	v_mul_f32_e32 v135, 0x45800000, v134
	v_cndmask_b32_e32 v182, v134, v135, vcc
	v_pk_mul_f32 v[132:133], v[132:133], v[182:183] op_sel_hi:[1,0]
	v_pk_mul_f32 v[136:137], v[136:137], v[182:183] op_sel_hi:[1,0]
	v_pk_mul_f32 v[134:135], v[186:187], v[132:133]
	v_pk_mul_f32 v[132:133], v[200:201], v[182:183] op_sel_hi:[1,0]
	v_pk_mul_f32 v[200:201], v[188:189], v[136:137]
	v_pk_mul_f32 v[204:205], v[190:191], v[132:133]
	v_pk_mul_f32 v[132:133], v[202:203], v[182:183] op_sel_hi:[1,0]
	v_pk_mul_f32 v[202:203], v[208:209], v[182:183] op_sel_hi:[1,0]
	v_and_b32_e32 v209, 0xfdf, v168
	v_pk_mul_f32 v[136:137], v[206:207], v[182:183] op_sel_hi:[1,0]
	v_pk_mul_f32 v[206:207], v[210:211], v[182:183] op_sel_hi:[1,0]
	v_lshlrev_b32_e32 v210, 8, v209
	v_mov_b32_e32 v211, v112
	v_lshl_add_u64 v[234:235], v[144:145], 0, v[210:211]
	global_load_dwordx4 v[210:213], v[234:235], off offset:16
	global_load_dwordx4 v[214:217], v[234:235], off
	v_pk_mul_f32 v[136:137], v[194:195], v[136:137]
	v_pk_mul_f32 v[130:131], v[130:131], v[182:183] op_sel_hi:[1,0]
	v_pk_mul_f32 v[132:133], v[192:193], v[132:133]
	v_pk_mul_f32 v[130:131], v[180:181], v[130:131]
	v_pk_mul_f32 v[206:207], v[198:199], v[206:207]
	v_pk_mul_f32 v[202:203], v[196:197], v[202:203]
	s_andn2_b64 vcc, exec, s[16:17]
	s_waitcnt vmcnt(0)
	v_mul_f32_e32 v173, v211, v130
	v_mul_f32_e32 v169, v215, v136
	v_fma_f32 v177, v214, v134, -v169
	v_mul_f32_e32 v169, v215, v134
	v_mul_f32_e32 v134, v217, v137
	v_fma_f32 v182, v216, v135, -v134
	v_mul_f32_e32 v134, v211, v132
	v_mul_f32_e32 v171, v217, v135
	v_fma_f32 v185, v210, v130, -v134
	v_mul_f32_e32 v130, v213, v133
	v_mul_f32_e32 v175, v213, v131
	v_fmac_f32_e32 v169, v214, v136
	v_fmac_f32_e32 v171, v216, v137
	v_fmac_f32_e32 v173, v210, v132
	v_fma_f32 v208, v212, v131, -v130
	v_fmac_f32_e32 v175, v212, v133
	global_load_dwordx4 v[130:133], v[234:235], off offset:144
	global_load_dwordx4 v[134:137], v[234:235], off offset:128
	s_waitcnt vmcnt(0)
	v_mul_f32_e32 v210, v135, v206
	v_mul_f32_e32 v135, v135, v204
	v_fma_f32 v210, v134, v204, -v210
	v_fmac_f32_e32 v135, v134, v206
	v_mul_f32_e32 v134, v137, v207
	v_fma_f32 v204, v136, v205, -v134
	v_mul_f32_e32 v134, v137, v205
	v_fmac_f32_e32 v134, v136, v207
	v_mul_f32_e32 v136, v131, v202
	v_mul_f32_e32 v131, v131, v200
	v_fma_f32 v136, v130, v200, -v136
	v_fmac_f32_e32 v131, v130, v202
	v_mul_f32_e32 v130, v133, v203
	v_fma_f32 v137, v132, v201, -v130
	v_mul_f32_e32 v130, v133, v201
	v_fmac_f32_e32 v130, v132, v203
	v_cndmask_b32_e64 v132, 0, 1, s[16:17]
	v_cmp_ne_u32_e64 s[0:1], 1, v132
	s_cbranch_vccnz .LBB0_591
	s_lshl_b32 s14, s2, 8
	s_lshl_b32 s15, s76, 7
	s_add_i32 s14, s14, s15
	v_lshrrev_b32_e32 v132, 5, v209
	v_or_b32_e32 v132, s14, v132
	v_ashrrev_i32_e32 v133, 31, v132
	v_lshlrev_b64 v[132:133], 12, v[132:133]
	v_lshl_add_u64 v[132:133], v[148:149], 0, v[132:133]
	s_mov_b64 s[36:37], 0
	v_cvt_pk_bf16_f32 v96, v177, v182
	v_cvt_pk_bf16_f32 v97, v185, v208
	v_cvt_pk_bf16_f32 v98, v210, v204
	v_cvt_pk_bf16_f32 v99, v136, v137
	v_cvt_pk_bf16_f32 v100, v169, v171
	v_cvt_pk_bf16_f32 v101, v173, v175
	v_cvt_pk_bf16_f32 v102, v135, v134
	v_cvt_pk_bf16_f32 v103, v131, v130
	v_mbcnt_lo_u32_b32 v104, -1, 0
	v_mbcnt_hi_u32_b32 v104, -1, v104
	v_and_b32_e32 v104, 16, v104
	v_mul_u32_u24_e32 v105, 63, v104
	v_lshrrev_b32_e32 v104, 1, v104
	v_add_u32_e32 v104, v104, v105
	v_mov_b32_e32 v105, 0
	v_permlane16_swap_b32_e32 v96, v98
	v_permlane16_swap_b32_e32 v97, v99
	v_permlane16_swap_b32_e32 v100, v102
	v_permlane16_swap_b32_e32 v101, v103
	v_lshl_add_u64 v[132:133], v[132:133], 0, v[104:105]
	global_store_dwordx4 v[132:133], v[96:99], off
	global_store_dwordx4 v[132:133], v[100:103], off offset:2048
; template <int EPI>
; __device__ __forceinline__ void gemm_epilogue(const f32x4 (&acc)[2][2][4][2], const Unit& u, int wr, int wc, int fr, int fq,
;                                               const EpiArgs& ea, const float (&rs_pre)[2][4]) {
;     ...
;       for (int ai = 0; ai < 2; ++ai)
; #pragma unroll
;         for (int m = 0; m < 4; ++m) {
;           const int row = row0 + ai * 128 + m * 16;
;           const float rs = rsr[ai][m];
;           f32x4 v[2][2];
;           float sq = 0.f;
; #pragma unroll
;           for (int bj = 0; bj < 2; ++bj)
; #pragma unroll
;             for (int n = 0; n < 2; ++n) {
;               v[bj][n] = acc[ai][bj][m][n] * rs;
;               sq += v[bj][n][0] * v[bj][n][0] + v[bj][n][1] * v[bj][n][1] + v[bj][n][2] * v[bj][n][2] + v[bj][n][3] * v[bj][n][3];
;             }
;           sq = xsum32(xsum16(sq));
;           const float hr = rsqrtf(sq * (1.f / 64.f) + EPS);
; #pragma unroll
;           for (int bj = 0; bj < 2; ++bj)
; #pragma unroll
;             for (int n = 0; n < 2; ++n) v[bj][n] = v[bj][n] * hr * gv[bj][n];
;           if constexpr (EPI == EPI_ODD) {
;             const int pos = row & 4095;
;             const float2* rope = reinterpret_cast<const float2*>(ea.aux_f2) + pos * 32 + 4 * fq;
; #pragma unroll
;             for (int n = 0; n < 2; ++n) {
;               f32x4 c01 = *reinterpret_cast<const f32x4*>(rope + n * 16);
;               f32x4 c23 = *reinterpret_cast<const f32x4*>(rope + n * 16 + 2);
;               float cs[4] = {c01[0], c01[2], c23[0], c23[2]}, sn[4] = {c01[1], c01[3], c23[1], c23[3]};
;               f32x4 x1 = v[0][n], x2 = v[1][n];
; #pragma unroll
;               for (int i = 0; i < 4; ++i) {
;                 v[0][n][i] = x1[i] * cs[i] - x2[i] * sn[i];
;                 v[1][n][i] = x2[i] * cs[i] + x1[i] * sn[i];
;               }
;             }
;           }
;           if (isq) {
; #pragma unroll
;             for (int bj = 0; bj < 2; ++bj)
; #pragma unroll
;               for (int n = 0; n < 2; ++n)
;                 *reinterpret_cast<uint2*>(ea.out_bf + (size_t)row * LD + lc0 + bj * 32 + n * 16) = pack4(v[bj][n]);
;           } else {
;             const int kh = unit - qhi, b = row >> 12, t = row & 4095;
;             u16* kb = ea.kp + ((size_t)((b * ea.nh + kh) * 128 + (t >> 5)) * 4) * 512 + ((fq >> 1) * 32 + (t & 31)) * 8 + (fq & 1) * 4;
; #pragma unroll
.LBB0_591:
	s_andn2_b64 vcc, exec, s[36:37]
	s_cbranch_vccnz .LBB0_593
	v_mov_b64_e32 v[200:201], s[42:43]
	v_mad_i64_i32 v[200:201], s[14:15], v168, s45, v[200:201]
	v_lshl_add_u64 v[200:201], v[178:179], 1, v[200:201]
	v_cvt_pk_bf16_f32 v96, v177, v182
	v_cvt_pk_bf16_f32 v97, v185, v208
	v_cvt_pk_bf16_f32 v98, v210, v204
	v_cvt_pk_bf16_f32 v99, v136, v137
	v_cvt_pk_bf16_f32 v100, v169, v171
	v_cvt_pk_bf16_f32 v101, v173, v175
	v_cvt_pk_bf16_f32 v102, v135, v134
	v_cvt_pk_bf16_f32 v103, v131, v130
	v_mbcnt_lo_u32_b32 v104, -1, 0
	v_mbcnt_hi_u32_b32 v104, -1, v104
	v_and_b32_e32 v104, 16, v104
	v_lshrrev_b32_e32 v105, 1, v104
	v_add_u32_e32 v104, v104, v105
	v_mov_b32_e32 v105, 0
	v_permlane16_swap_b32_e32 v96, v98
	v_permlane16_swap_b32_e32 v97, v99
	v_permlane16_swap_b32_e32 v100, v102
	v_permlane16_swap_b32_e32 v101, v103
	v_lshl_add_u64 v[200:201], v[200:201], 0, v[104:105]
	global_store_dwordx4 v[200:201], v[96:99], off
	global_store_dwordx4 v[200:201], v[100:103], off offset:64
.LBB0_593:
	v_pk_mul_f32 v[132:133], v[92:93], v[170:171] op_sel_hi:[1,0]
	v_pk_mul_f32 v[200:201], v[88:89], v[170:171] op_sel_hi:[1,0]
	v_mul_f32_e32 v134, v133, v133
	v_mul_f32_e32 v135, v201, v201
	v_pk_mul_f32 v[130:131], v[94:95], v[170:171] op_sel_hi:[1,0]
	v_fmac_f32_e32 v134, v132, v132
	v_pk_mul_f32 v[136:137], v[90:91], v[170:171] op_sel_hi:[1,0]
	v_fmac_f32_e32 v135, v200, v200
	v_fmac_f32_e32 v134, v130, v130
	v_fmac_f32_e32 v135, v136, v136
	v_fmac_f32_e32 v134, v131, v131
	v_fmac_f32_e32 v135, v137, v137
	v_pk_mul_f32 v[206:207], v[84:85], v[170:171] op_sel_hi:[1,0]
	v_add_f32_e32 v134, v134, v135
	v_mul_f32_e32 v135, v207, v207
	v_pk_mul_f32 v[202:203], v[86:87], v[170:171] op_sel_hi:[1,0]
	v_fmac_f32_e32 v135, v206, v206
	v_fmac_f32_e32 v135, v202, v202
	v_fmac_f32_e32 v135, v203, v203
	v_pk_mul_f32 v[210:211], v[80:81], v[170:171] op_sel_hi:[1,0]
	v_add_f32_e32 v134, v135, v134
	v_mul_f32_e32 v135, v211, v211
	v_pk_mul_f32 v[208:209], v[82:83], v[170:171] op_sel_hi:[1,0]
	v_fmac_f32_e32 v135, v210, v210
	v_fmac_f32_e32 v135, v208, v208
	v_fmac_f32_e32 v135, v209, v209
	v_add_f32_e32 v134, v135, v134
	v_mov_b32_e32 v135, v134
	s_nop 1
	v_permlane16_swap_b32_e32 v134, v135
	v_add_f32_e32 v134, v134, v135
	v_mov_b32_e32 v135, v134
	s_nop 1
	v_permlane32_swap_b32_e32 v134, v135
	v_add_f32_e32 v134, v134, v135
	v_fmamk_f32 v134, v134, 0x3c800000, v218
	v_cmp_gt_f32_e32 vcc, s26, v134
	v_mul_f32_e32 v135, 0x4b800000, v134
	s_mov_b64 s[36:37], -1
	v_cndmask_b32_e32 v134, v134, v135, vcc
	v_rsq_f32_e32 v134, v134
	s_nop 0
	v_mul_f32_e32 v135, 0x45800000, v134
	v_cndmask_b32_e32 v182, v134, v135, vcc
	v_pk_mul_f32 v[132:133], v[132:133], v[182:183] op_sel_hi:[1,0]
	v_pk_mul_f32 v[136:137], v[136:137], v[182:183] op_sel_hi:[1,0]
	v_pk_mul_f32 v[134:135], v[186:187], v[132:133]
	v_pk_mul_f32 v[132:133], v[200:201], v[182:183] op_sel_hi:[1,0]
	v_pk_mul_f32 v[200:201], v[188:189], v[136:137]
	v_pk_mul_f32 v[204:205], v[190:191], v[132:133]
	v_pk_mul_f32 v[132:133], v[202:203], v[182:183] op_sel_hi:[1,0]
	v_pk_mul_f32 v[202:203], v[208:209], v[182:183] op_sel_hi:[1,0]
	v_and_b32_e32 v209, 0xfef, v164
	v_pk_mul_f32 v[136:137], v[206:207], v[182:183] op_sel_hi:[1,0]
	v_pk_mul_f32 v[206:207], v[210:211], v[182:183] op_sel_hi:[1,0]
	v_lshlrev_b32_e32 v210, 8, v209
	v_mov_b32_e32 v211, v112
	v_lshl_add_u64 v[234:235], v[144:145], 0, v[210:211]
	global_load_dwordx4 v[210:213], v[234:235], off offset:16
	global_load_dwordx4 v[214:217], v[234:235], off
	v_pk_mul_f32 v[136:137], v[194:195], v[136:137]
	v_pk_mul_f32 v[130:131], v[130:131], v[182:183] op_sel_hi:[1,0]
	v_pk_mul_f32 v[132:133], v[192:193], v[132:133]
	v_pk_mul_f32 v[130:131], v[180:181], v[130:131]
	v_pk_mul_f32 v[206:207], v[198:199], v[206:207]
	v_pk_mul_f32 v[202:203], v[196:197], v[202:203]
	s_and_b64 vcc, exec, s[0:1]
	s_waitcnt vmcnt(0)
	v_mul_f32_e32 v173, v211, v130
	v_mul_f32_e32 v169, v215, v136
	v_fma_f32 v177, v214, v134, -v169
	v_mul_f32_e32 v169, v215, v134
	v_mul_f32_e32 v134, v217, v137
	v_fma_f32 v182, v216, v135, -v134
	v_mul_f32_e32 v134, v211, v132
	v_mul_f32_e32 v171, v217, v135
	v_fma_f32 v185, v210, v130, -v134
	v_mul_f32_e32 v130, v213, v133
	v_mul_f32_e32 v175, v213, v131
	v_fmac_f32_e32 v169, v214, v136
	v_fmac_f32_e32 v171, v216, v137
	v_fmac_f32_e32 v173, v210, v132
	v_fma_f32 v208, v212, v131, -v130
	v_fmac_f32_e32 v175, v212, v133
	global_load_dwordx4 v[130:133], v[234:235], off offset:144
	global_load_dwordx4 v[134:137], v[234:235], off offset:128
	s_waitcnt vmcnt(0)
	v_mul_f32_e32 v210, v135, v206
	v_mul_f32_e32 v135, v135, v204
	v_fma_f32 v210, v134, v204, -v210
	v_fmac_f32_e32 v135, v134, v206
	v_mul_f32_e32 v134, v137, v207
	v_fma_f32 v204, v136, v205, -v134
	v_mul_f32_e32 v134, v137, v205
	v_fmac_f32_e32 v134, v136, v207
	v_mul_f32_e32 v136, v131, v202
	v_mul_f32_e32 v131, v131, v200
	v_fma_f32 v136, v130, v200, -v136
	v_fmac_f32_e32 v131, v130, v202
	v_mul_f32_e32 v130, v133, v203
	v_fma_f32 v137, v132, v201, -v130
	v_mul_f32_e32 v130, v133, v201
	v_fmac_f32_e32 v130, v132, v203
	s_cbranch_vccnz .LBB0_595
	s_lshl_b32 s14, s2, 8
	s_lshl_b32 s15, s76, 7
	s_add_i32 s14, s14, s15
	v_lshrrev_b32_e32 v132, 5, v209
	v_or_b32_e32 v132, s14, v132
	v_ashrrev_i32_e32 v133, 31, v132
	v_lshlrev_b64 v[132:133], 12, v[132:133]
	v_lshl_add_u64 v[132:133], v[146:147], 0, v[132:133]
	s_mov_b64 s[36:37], 0
	v_cvt_pk_bf16_f32 v80, v177, v182
	v_cvt_pk_bf16_f32 v81, v185, v208
	v_cvt_pk_bf16_f32 v82, v210, v204
	v_cvt_pk_bf16_f32 v83, v136, v137
	v_cvt_pk_bf16_f32 v84, v169, v171
	v_cvt_pk_bf16_f32 v85, v173, v175
	v_cvt_pk_bf16_f32 v86, v135, v134
	v_cvt_pk_bf16_f32 v87, v131, v130
	v_mbcnt_lo_u32_b32 v88, -1, 0
	v_mbcnt_hi_u32_b32 v88, -1, v88
	v_and_b32_e32 v88, 16, v88
	v_mul_u32_u24_e32 v89, 63, v88
	v_lshrrev_b32_e32 v88, 1, v88
	v_add_u32_e32 v88, v88, v89
	v_mov_b32_e32 v89, 0
	v_permlane16_swap_b32_e32 v80, v82
	v_permlane16_swap_b32_e32 v81, v83
	v_permlane16_swap_b32_e32 v84, v86
	v_permlane16_swap_b32_e32 v85, v87
	v_lshl_add_u64 v[132:133], v[132:133], 0, v[88:89]
	global_store_dwordx4 v[132:133], v[80:83], off
	global_store_dwordx4 v[132:133], v[84:87], off offset:2048
; template <int EPI>
; __device__ __forceinline__ void gemm_epilogue(const f32x4 (&acc)[2][2][4][2], const Unit& u, int wr, int wc, int fr, int fq,
;                                               const EpiArgs& ea, const float (&rs_pre)[2][4]) {
;     ...
;       for (int ai = 0; ai < 2; ++ai)
; #pragma unroll
;         for (int m = 0; m < 4; ++m) {
;           const int row = row0 + ai * 128 + m * 16;
;           const float rs = rsr[ai][m];
;           f32x4 v[2][2];
;           float sq = 0.f;
; #pragma unroll
;           for (int bj = 0; bj < 2; ++bj)
; #pragma unroll
;             for (int n = 0; n < 2; ++n) {
;               v[bj][n] = acc[ai][bj][m][n] * rs;
;               sq += v[bj][n][0] * v[bj][n][0] + v[bj][n][1] * v[bj][n][1] + v[bj][n][2] * v[bj][n][2] + v[bj][n][3] * v[bj][n][3];
;             }
;           sq = xsum32(xsum16(sq));
;           const float hr = rsqrtf(sq * (1.f / 64.f) + EPS);
; #pragma unroll
;           for (int bj = 0; bj < 2; ++bj)
; #pragma unroll
;             for (int n = 0; n < 2; ++n) v[bj][n] = v[bj][n] * hr * gv[bj][n];
;           if constexpr (EPI == EPI_ODD) {
;             const int pos = row & 4095;
;             const float2* rope = reinterpret_cast<const float2*>(ea.aux_f2) + pos * 32 + 4 * fq;
; #pragma unroll
;             for (int n = 0; n < 2; ++n) {
;               f32x4 c01 = *reinterpret_cast<const f32x4*>(rope + n * 16);
;               f32x4 c23 = *reinterpret_cast<const f32x4*>(rope + n * 16 + 2);
;               float cs[4] = {c01[0], c01[2], c23[0], c23[2]}, sn[4] = {c01[1], c01[3], c23[1], c23[3]};
;               f32x4 x1 = v[0][n], x2 = v[1][n];
; #pragma unroll
;               for (int i = 0; i < 4; ++i) {
;                 v[0][n][i] = x1[i] * cs[i] - x2[i] * sn[i];
;                 v[1][n][i] = x2[i] * cs[i] + x1[i] * sn[i];
;               }
;             }
;           }
;           if (isq) {
; #pragma unroll
;             for (int bj = 0; bj < 2; ++bj)
; #pragma unroll
;               for (int n = 0; n < 2; ++n)
;                 *reinterpret_cast<uint2*>(ea.out_bf + (size_t)row * LD + lc0 + bj * 32 + n * 16) = pack4(v[bj][n]);
;           } else {
;             const int kh = unit - qhi, b = row >> 12, t = row & 4095;
;             u16* kb = ea.kp + ((size_t)((b * ea.nh + kh) * 128 + (t >> 5)) * 4) * 512 + ((fq >> 1) * 32 + (t & 31)) * 8 + (fq & 1) * 4;
; #pragma unroll
.LBB0_595:
	s_andn2_b64 vcc, exec, s[36:37]
	s_cbranch_vccnz .LBB0_597
	v_mov_b64_e32 v[200:201], s[42:43]
	v_mad_i64_i32 v[200:201], s[14:15], v164, s45, v[200:201]
	v_lshl_add_u64 v[200:201], v[178:179], 1, v[200:201]
	v_cvt_pk_bf16_f32 v80, v177, v182
	v_cvt_pk_bf16_f32 v81, v185, v208
	v_cvt_pk_bf16_f32 v82, v210, v204
	v_cvt_pk_bf16_f32 v83, v136, v137
	v_cvt_pk_bf16_f32 v84, v169, v171
	v_cvt_pk_bf16_f32 v85, v173, v175
	v_cvt_pk_bf16_f32 v86, v135, v134
	v_cvt_pk_bf16_f32 v87, v131, v130
	v_mbcnt_lo_u32_b32 v88, -1, 0
	v_mbcnt_hi_u32_b32 v88, -1, v88
	v_and_b32_e32 v88, 16, v88
	v_lshrrev_b32_e32 v89, 1, v88
	v_add_u32_e32 v88, v88, v89
	v_mov_b32_e32 v89, 0
	v_permlane16_swap_b32_e32 v80, v82
	v_permlane16_swap_b32_e32 v81, v83
	v_permlane16_swap_b32_e32 v84, v86
	v_permlane16_swap_b32_e32 v85, v87
	v_lshl_add_u64 v[200:201], v[200:201], 0, v[88:89]
	global_store_dwordx4 v[200:201], v[80:83], off
	global_store_dwordx4 v[200:201], v[84:87], off offset:64
.LBB0_597:
	v_pk_mul_f32 v[132:133], v[76:77], v[166:167] op_sel_hi:[1,0]
	v_pk_mul_f32 v[200:201], v[72:73], v[166:167] op_sel_hi:[1,0]
	v_mul_f32_e32 v134, v133, v133
	v_mul_f32_e32 v135, v201, v201
	v_pk_mul_f32 v[130:131], v[78:79], v[166:167] op_sel_hi:[1,0]
	v_fmac_f32_e32 v134, v132, v132
	v_pk_mul_f32 v[136:137], v[74:75], v[166:167] op_sel_hi:[1,0]
	v_fmac_f32_e32 v135, v200, v200
	v_fmac_f32_e32 v134, v130, v130
	v_fmac_f32_e32 v135, v136, v136
	v_fmac_f32_e32 v134, v131, v131
	v_fmac_f32_e32 v135, v137, v137
	v_pk_mul_f32 v[206:207], v[68:69], v[166:167] op_sel_hi:[1,0]
	v_add_f32_e32 v134, v134, v135
	v_mul_f32_e32 v135, v207, v207
	v_pk_mul_f32 v[202:203], v[70:71], v[166:167] op_sel_hi:[1,0]
	v_fmac_f32_e32 v135, v206, v206
	v_fmac_f32_e32 v135, v202, v202
	v_fmac_f32_e32 v135, v203, v203
	v_pk_mul_f32 v[210:211], v[64:65], v[166:167] op_sel_hi:[1,0]
	v_add_f32_e32 v134, v135, v134
	v_mul_f32_e32 v135, v211, v211
	v_pk_mul_f32 v[208:209], v[66:67], v[166:167] op_sel_hi:[1,0]
	v_fmac_f32_e32 v135, v210, v210
	v_fmac_f32_e32 v135, v208, v208
	v_fmac_f32_e32 v135, v209, v209
	v_add_f32_e32 v134, v135, v134
	v_mov_b32_e32 v135, v134
	s_nop 1
	v_permlane16_swap_b32_e32 v134, v135
	v_add_f32_e32 v134, v134, v135
	v_mov_b32_e32 v135, v134
	s_nop 1
	v_permlane32_swap_b32_e32 v134, v135
	v_add_f32_e32 v134, v134, v135
	v_fmamk_f32 v134, v134, 0x3c800000, v218
	v_cmp_gt_f32_e32 vcc, s26, v134
	v_mul_f32_e32 v135, 0x4b800000, v134
	s_mov_b64 s[36:37], -1
	v_cndmask_b32_e32 v134, v134, v135, vcc
	v_rsq_f32_e32 v134, v134
	s_nop 0
	v_mul_f32_e32 v135, 0x45800000, v134
	v_cndmask_b32_e32 v182, v134, v135, vcc
	v_pk_mul_f32 v[132:133], v[132:133], v[182:183] op_sel_hi:[1,0]
	v_pk_mul_f32 v[136:137], v[136:137], v[182:183] op_sel_hi:[1,0]
	v_pk_mul_f32 v[134:135], v[186:187], v[132:133]
	v_pk_mul_f32 v[132:133], v[200:201], v[182:183] op_sel_hi:[1,0]
	v_pk_mul_f32 v[200:201], v[188:189], v[136:137]
	v_pk_mul_f32 v[204:205], v[190:191], v[132:133]
	v_pk_mul_f32 v[132:133], v[202:203], v[182:183] op_sel_hi:[1,0]
	v_pk_mul_f32 v[202:203], v[208:209], v[182:183] op_sel_hi:[1,0]
	v_and_b32_e32 v209, 0xfff, v160
	v_pk_mul_f32 v[136:137], v[206:207], v[182:183] op_sel_hi:[1,0]
	v_pk_mul_f32 v[206:207], v[210:211], v[182:183] op_sel_hi:[1,0]
	v_lshlrev_b32_e32 v210, 8, v209
	v_mov_b32_e32 v211, v112
	v_lshl_add_u64 v[234:235], v[144:145], 0, v[210:211]
	global_load_dwordx4 v[210:213], v[234:235], off offset:16
	global_load_dwordx4 v[214:217], v[234:235], off
	v_pk_mul_f32 v[136:137], v[194:195], v[136:137]
	v_pk_mul_f32 v[130:131], v[130:131], v[182:183] op_sel_hi:[1,0]
	v_pk_mul_f32 v[132:133], v[192:193], v[132:133]
	v_pk_mul_f32 v[130:131], v[180:181], v[130:131]
	v_pk_mul_f32 v[206:207], v[198:199], v[206:207]
	v_pk_mul_f32 v[202:203], v[196:197], v[202:203]
	s_and_b64 vcc, exec, s[0:1]
	s_waitcnt vmcnt(0)
	v_mul_f32_e32 v173, v211, v130
	v_mul_f32_e32 v169, v215, v136
	v_fma_f32 v177, v214, v134, -v169
	v_mul_f32_e32 v169, v215, v134
	v_mul_f32_e32 v134, v217, v137
	v_fma_f32 v182, v216, v135, -v134
	v_mul_f32_e32 v134, v211, v132
	v_mul_f32_e32 v171, v217, v135
	v_fma_f32 v185, v210, v130, -v134
	v_mul_f32_e32 v130, v213, v133
	v_mul_f32_e32 v175, v213, v131
	v_fmac_f32_e32 v169, v214, v136
	v_fmac_f32_e32 v171, v216, v137
	v_fmac_f32_e32 v173, v210, v132
	v_fma_f32 v208, v212, v131, -v130
	v_fmac_f32_e32 v175, v212, v133
	global_load_dwordx4 v[130:133], v[234:235], off offset:144
	global_load_dwordx4 v[134:137], v[234:235], off offset:128
	s_waitcnt vmcnt(0)
	v_mul_f32_e32 v210, v135, v206
	v_mul_f32_e32 v135, v135, v204
	v_fma_f32 v210, v134, v204, -v210
	v_fmac_f32_e32 v135, v134, v206
	v_mul_f32_e32 v134, v137, v207
	v_fma_f32 v204, v136, v205, -v134
	v_mul_f32_e32 v134, v137, v205
	v_fmac_f32_e32 v134, v136, v207
	v_mul_f32_e32 v136, v131, v202
	v_mul_f32_e32 v131, v131, v200
	v_fma_f32 v136, v130, v200, -v136
	v_fmac_f32_e32 v131, v130, v202
	v_mul_f32_e32 v130, v133, v203
	v_fma_f32 v137, v132, v201, -v130
	v_mul_f32_e32 v130, v133, v201
	v_fmac_f32_e32 v130, v132, v203
	s_cbranch_vccnz .LBB0_599
	s_lshl_b32 s2, s2, 8
	s_lshl_b32 s14, s76, 7
	s_add_i32 s2, s2, s14
	v_lshrrev_b32_e32 v132, 5, v209
	v_or_b32_e32 v132, s2, v132
	v_ashrrev_i32_e32 v133, 31, v132
	v_lshlrev_b64 v[132:133], 12, v[132:133]
	v_lshl_add_u64 v[132:133], v[148:149], 0, v[132:133]
	s_mov_b64 s[36:37], 0
	v_cvt_pk_bf16_f32 v64, v177, v182
	v_cvt_pk_bf16_f32 v65, v185, v208
	v_cvt_pk_bf16_f32 v66, v210, v204
	v_cvt_pk_bf16_f32 v67, v136, v137
	v_cvt_pk_bf16_f32 v68, v169, v171
	v_cvt_pk_bf16_f32 v69, v173, v175
	v_cvt_pk_bf16_f32 v70, v135, v134
	v_cvt_pk_bf16_f32 v71, v131, v130
	v_mbcnt_lo_u32_b32 v72, -1, 0
	v_mbcnt_hi_u32_b32 v72, -1, v72
	v_and_b32_e32 v72, 16, v72
	v_mul_u32_u24_e32 v73, 63, v72
	v_lshrrev_b32_e32 v72, 1, v72
	v_add_u32_e32 v72, v72, v73
	v_mov_b32_e32 v73, 0
	v_permlane16_swap_b32_e32 v64, v66
	v_permlane16_swap_b32_e32 v65, v67
	v_permlane16_swap_b32_e32 v68, v70
	v_permlane16_swap_b32_e32 v69, v71
	v_lshl_add_u64 v[132:133], v[132:133], 0, v[72:73]
	global_store_dwordx4 v[132:133], v[64:67], off
	global_store_dwordx4 v[132:133], v[68:71], off offset:2048
; template <int EPI>
; __device__ __forceinline__ void gemm_epilogue(const f32x4 (&acc)[2][2][4][2], const Unit& u, int wr, int wc, int fr, int fq,
;                                               const EpiArgs& ea, const float (&rs_pre)[2][4]) {
;     ...
;         for (int m = 0; m < 4; ++m) {
;           const int row = row0 + ai * 128 + m * 16;
;           const float rs = rsr[ai][m];
;           f32x4 v[2][2];
;           float sq = 0.f;
; #pragma unroll
;           for (int bj = 0; bj < 2; ++bj)
; #pragma unroll
;             for (int n = 0; n < 2; ++n) {
;               v[bj][n] = acc[ai][bj][m][n] * rs;
;               sq += v[bj][n][0] * v[bj][n][0] + v[bj][n][1] * v[bj][n][1] + v[bj][n][2] * v[bj][n][2] + v[bj][n][3] * v[bj][n][3];
;             }
;           sq = xsum32(xsum16(sq));
;           const float hr = rsqrtf(sq * (1.f / 64.f) + EPS);
; #pragma unroll
;           for (int bj = 0; bj < 2; ++bj)
; #pragma unroll
;             for (int n = 0; n < 2; ++n) v[bj][n] = v[bj][n] * hr * gv[bj][n];
;           if constexpr (EPI == EPI_ODD) {
;             const int pos = row & 4095;
;             const float2* rope = reinterpret_cast<const float2*>(ea.aux_f2) + pos * 32 + 4 * fq;
; #pragma unroll
;             for (int n = 0; n < 2; ++n) {
;               f32x4 c01 = *reinterpret_cast<const f32x4*>(rope + n * 16);
;               f32x4 c23 = *reinterpret_cast<const f32x4*>(rope + n * 16 + 2);
;               float cs[4] = {c01[0], c01[2], c23[0], c23[2]}, sn[4] = {c01[1], c01[3], c23[1], c23[3]};
;               f32x4 x1 = v[0][n], x2 = v[1][n];
; #pragma unroll
;               for (int i = 0; i < 4; ++i) {
;                 v[0][n][i] = x1[i] * cs[i] - x2[i] * sn[i];
;                 v[1][n][i] = x2[i] * cs[i] + x1[i] * sn[i];
;               }
;             }
;           }
;           if (isq) {
; #pragma unroll
;             for (int bj = 0; bj < 2; ++bj)
; #pragma unroll
;               for (int n = 0; n < 2; ++n)
;                 *reinterpret_cast<uint2*>(ea.out_bf + (size_t)row * LD + lc0 + bj * 32 + n * 16) = pack4(v[bj][n]);
;           } else {
;             const int kh = unit - qhi, b = row >> 12, t = row & 4095;
;             u16* kb = ea.kp + ((size_t)((b * ea.nh + kh) * 128 + (t >> 5)) * 4) * 512 + ((fq >> 1) * 32 + (t & 31)) * 8 + (fq & 1) * 4;
; #pragma unroll
;             for (int bj = 0; bj < 2; ++bj)
; #pragma unroll
.LBB0_599:
	s_andn2_b64 vcc, exec, s[36:37]
	s_cbranch_vccnz .LBB0_601
	v_mov_b64_e32 v[200:201], s[42:43]
	v_mad_i64_i32 v[200:201], s[14:15], v160, s45, v[200:201]
	v_lshl_add_u64 v[200:201], v[178:179], 1, v[200:201]
	v_cvt_pk_bf16_f32 v64, v177, v182
	v_cvt_pk_bf16_f32 v65, v185, v208
	v_cvt_pk_bf16_f32 v66, v210, v204
	v_cvt_pk_bf16_f32 v67, v136, v137
	v_cvt_pk_bf16_f32 v68, v169, v171
	v_cvt_pk_bf16_f32 v69, v173, v175
	v_cvt_pk_bf16_f32 v70, v135, v134
	v_cvt_pk_bf16_f32 v71, v131, v130
	v_mbcnt_lo_u32_b32 v72, -1, 0
	v_mbcnt_hi_u32_b32 v72, -1, v72
	v_and_b32_e32 v72, 16, v72
	v_lshrrev_b32_e32 v73, 1, v72
	v_add_u32_e32 v72, v72, v73
	v_mov_b32_e32 v73, 0
	v_permlane16_swap_b32_e32 v64, v66
	v_permlane16_swap_b32_e32 v65, v67
	v_permlane16_swap_b32_e32 v68, v70
	v_permlane16_swap_b32_e32 v69, v71
	v_lshl_add_u64 v[200:201], v[200:201], 0, v[72:73]
	global_store_dwordx4 v[200:201], v[64:67], off
	global_store_dwordx4 v[200:201], v[68:71], off offset:64
.LBB0_601:
	v_pk_mul_f32 v[132:133], v[60:61], v[162:163] op_sel_hi:[1,0]
	v_pk_mul_f32 v[200:201], v[56:57], v[162:163] op_sel_hi:[1,0]
	v_mul_f32_e32 v134, v133, v133
	v_mul_f32_e32 v135, v201, v201
	v_pk_mul_f32 v[130:131], v[62:63], v[162:163] op_sel_hi:[1,0]
	v_fmac_f32_e32 v134, v132, v132
	v_pk_mul_f32 v[136:137], v[58:59], v[162:163] op_sel_hi:[1,0]
	v_fmac_f32_e32 v135, v200, v200
	v_fmac_f32_e32 v134, v130, v130
	v_fmac_f32_e32 v135, v136, v136
	v_fmac_f32_e32 v134, v131, v131
	v_fmac_f32_e32 v135, v137, v137
	v_pk_mul_f32 v[206:207], v[52:53], v[162:163] op_sel_hi:[1,0]
	v_add_f32_e32 v134, v134, v135
	v_mul_f32_e32 v135, v207, v207
	v_pk_mul_f32 v[202:203], v[54:55], v[162:163] op_sel_hi:[1,0]
	v_fmac_f32_e32 v135, v206, v206
	v_fmac_f32_e32 v135, v202, v202
	v_fmac_f32_e32 v135, v203, v203
	v_pk_mul_f32 v[210:211], v[48:49], v[162:163] op_sel_hi:[1,0]
	v_add_f32_e32 v134, v135, v134
	v_mul_f32_e32 v135, v211, v211
	v_pk_mul_f32 v[208:209], v[50:51], v[162:163] op_sel_hi:[1,0]
	v_fmac_f32_e32 v135, v210, v210
	v_fmac_f32_e32 v135, v208, v208
	v_fmac_f32_e32 v135, v209, v209
	v_add_f32_e32 v134, v135, v134
	v_mov_b32_e32 v135, v134
	s_nop 1
	v_permlane16_swap_b32_e32 v134, v135
	v_add_f32_e32 v134, v134, v135
	v_mov_b32_e32 v135, v134
	s_nop 1
	v_permlane32_swap_b32_e32 v134, v135
	v_add_f32_e32 v134, v134, v135
	v_fmamk_f32 v134, v134, 0x3c800000, v218
	v_cmp_gt_f32_e32 vcc, s26, v134
	v_mul_f32_e32 v135, 0x4b800000, v134
	v_ashrrev_i32_e32 v169, 12, v167
	v_cndmask_b32_e32 v134, v134, v135, vcc
	v_rsq_f32_e32 v134, v134
	s_mov_b64 s[36:37], -1
	v_mul_f32_e32 v135, 0x45800000, v134
	v_cndmask_b32_e32 v182, v134, v135, vcc
	v_pk_mul_f32 v[132:133], v[132:133], v[182:183] op_sel_hi:[1,0]
	v_pk_mul_f32 v[136:137], v[136:137], v[182:183] op_sel_hi:[1,0]
	v_pk_mul_f32 v[134:135], v[186:187], v[132:133]
	v_pk_mul_f32 v[132:133], v[200:201], v[182:183] op_sel_hi:[1,0]
	v_pk_mul_f32 v[200:201], v[188:189], v[136:137]
	v_pk_mul_f32 v[136:137], v[206:207], v[182:183] op_sel_hi:[1,0]
	v_pk_mul_f32 v[206:207], v[210:211], v[182:183] op_sel_hi:[1,0]
	v_and_b32_e32 v210, 0xfcf, v167
	v_pk_mul_f32 v[204:205], v[190:191], v[132:133]
	v_pk_mul_f32 v[132:133], v[202:203], v[182:183] op_sel_hi:[1,0]
	v_pk_mul_f32 v[202:203], v[208:209], v[182:183] op_sel_hi:[1,0]
	v_lshlrev_b32_e32 v208, 8, v210
	v_mov_b32_e32 v209, v112
	v_lshl_add_u64 v[216:217], v[144:145], 0, v[208:209]
	global_load_dwordx4 v[212:215], v[216:217], off offset:16
	global_load_dwordx4 v[236:239], v[216:217], off
	v_pk_mul_f32 v[136:137], v[194:195], v[136:137]
	v_pk_mul_f32 v[130:131], v[130:131], v[182:183] op_sel_hi:[1,0]
	v_pk_mul_f32 v[132:133], v[192:193], v[132:133]
	v_pk_mul_f32 v[130:131], v[180:181], v[130:131]
	v_pk_mul_f32 v[206:207], v[198:199], v[206:207]
	v_pk_mul_f32 v[202:203], v[196:197], v[202:203]
	s_and_b64 vcc, exec, s[0:1]
	s_waitcnt vmcnt(0)
	v_mul_f32_e32 v175, v213, v130
	v_mul_f32_e32 v171, v237, v136
	v_fma_f32 v182, v236, v134, -v171
	v_mul_f32_e32 v171, v237, v134
	v_mul_f32_e32 v134, v239, v137
	v_fma_f32 v185, v238, v135, -v134
	v_mul_f32_e32 v134, v213, v132
	v_mul_f32_e32 v173, v239, v135
	v_fma_f32 v208, v212, v130, -v134
	v_mul_f32_e32 v130, v215, v133
	v_mul_f32_e32 v177, v215, v131
	v_fmac_f32_e32 v171, v236, v136
	v_fmac_f32_e32 v173, v238, v137
	v_fmac_f32_e32 v175, v212, v132
	v_fma_f32 v209, v214, v131, -v130
	v_fmac_f32_e32 v177, v214, v133
	global_load_dwordx4 v[130:133], v[216:217], off offset:144
	global_load_dwordx4 v[134:137], v[216:217], off offset:128
	s_waitcnt vmcnt(0)
	v_mul_f32_e32 v211, v135, v206
	v_mul_f32_e32 v135, v135, v204
	v_fma_f32 v211, v134, v204, -v211
	v_fmac_f32_e32 v135, v134, v206
	v_mul_f32_e32 v134, v137, v207
	v_fma_f32 v204, v136, v205, -v134
	v_mul_f32_e32 v134, v137, v205
	v_fmac_f32_e32 v134, v136, v207
	v_mul_f32_e32 v136, v131, v202
	v_mul_f32_e32 v131, v131, v200
	v_fma_f32 v136, v130, v200, -v136
	v_fmac_f32_e32 v131, v130, v202
	v_mul_f32_e32 v130, v133, v203
	v_fma_f32 v137, v132, v201, -v130
	v_mul_f32_e32 v130, v133, v201
	v_fmac_f32_e32 v130, v132, v203
	s_cbranch_vccnz .LBB0_603
	s_lshl_b32 s2, s76, 7
	v_lshl_add_u32 v132, v169, 8, s2
	v_lshrrev_b32_e32 v133, 5, v210
	v_or_b32_e32 v132, v132, v133
	v_ashrrev_i32_e32 v133, 31, v132
	v_lshlrev_b64 v[132:133], 12, v[132:133]
	v_lshl_add_u64 v[132:133], v[146:147], 0, v[132:133]
	s_mov_b64 s[36:37], 0
	v_cvt_pk_bf16_f32 v48, v182, v185
	v_cvt_pk_bf16_f32 v49, v208, v209
	v_cvt_pk_bf16_f32 v50, v211, v204
	v_cvt_pk_bf16_f32 v51, v136, v137
	v_cvt_pk_bf16_f32 v52, v171, v173
	v_cvt_pk_bf16_f32 v53, v175, v177
	v_cvt_pk_bf16_f32 v54, v135, v134
	v_cvt_pk_bf16_f32 v55, v131, v130
	v_mbcnt_lo_u32_b32 v56, -1, 0
	v_mbcnt_hi_u32_b32 v56, -1, v56
	v_and_b32_e32 v56, 16, v56
	v_mul_u32_u24_e32 v57, 63, v56
	v_lshrrev_b32_e32 v56, 1, v56
	v_add_u32_e32 v56, v56, v57
	v_mov_b32_e32 v57, 0
	v_permlane16_swap_b32_e32 v48, v50
	v_permlane16_swap_b32_e32 v49, v51
	v_permlane16_swap_b32_e32 v52, v54
	v_permlane16_swap_b32_e32 v53, v55
	v_lshl_add_u64 v[132:133], v[132:133], 0, v[56:57]
	global_store_dwordx4 v[132:133], v[48:51], off
	global_store_dwordx4 v[132:133], v[52:55], off offset:2048
; template <int EPI>
; __device__ __forceinline__ void gemm_epilogue(const f32x4 (&acc)[2][2][4][2], const Unit& u, int wr, int wc, int fr, int fq,
;                                               const EpiArgs& ea, const float (&rs_pre)[2][4]) {
;     ...
;         for (int m = 0; m < 4; ++m) {
;           const int row = row0 + ai * 128 + m * 16;
;           const float rs = rsr[ai][m];
;           f32x4 v[2][2];
;           float sq = 0.f;
; #pragma unroll
;           for (int bj = 0; bj < 2; ++bj)
; #pragma unroll
;             for (int n = 0; n < 2; ++n) {
;               v[bj][n] = acc[ai][bj][m][n] * rs;
;               sq += v[bj][n][0] * v[bj][n][0] + v[bj][n][1] * v[bj][n][1] + v[bj][n][2] * v[bj][n][2] + v[bj][n][3] * v[bj][n][3];
;             }
;           sq = xsum32(xsum16(sq));
;           const float hr = rsqrtf(sq * (1.f / 64.f) + EPS);
; #pragma unroll
;           for (int bj = 0; bj < 2; ++bj)
; #pragma unroll
;             for (int n = 0; n < 2; ++n) v[bj][n] = v[bj][n] * hr * gv[bj][n];
;           if constexpr (EPI == EPI_ODD) {
;             const int pos = row & 4095;
;             const float2* rope = reinterpret_cast<const float2*>(ea.aux_f2) + pos * 32 + 4 * fq;
; #pragma unroll
;             for (int n = 0; n < 2; ++n) {
;               f32x4 c01 = *reinterpret_cast<const f32x4*>(rope + n * 16);
;               f32x4 c23 = *reinterpret_cast<const f32x4*>(rope + n * 16 + 2);
;               float cs[4] = {c01[0], c01[2], c23[0], c23[2]}, sn[4] = {c01[1], c01[3], c23[1], c23[3]};
;               f32x4 x1 = v[0][n], x2 = v[1][n];
; #pragma unroll
;               for (int i = 0; i < 4; ++i) {
;                 v[0][n][i] = x1[i] * cs[i] - x2[i] * sn[i];
;                 v[1][n][i] = x2[i] * cs[i] + x1[i] * sn[i];
;               }
;             }
;           }
;           if (isq) {
; #pragma unroll
;             for (int bj = 0; bj < 2; ++bj)
; #pragma unroll
;               for (int n = 0; n < 2; ++n)
;                 *reinterpret_cast<uint2*>(ea.out_bf + (size_t)row * LD + lc0 + bj * 32 + n * 16) = pack4(v[bj][n]);
;           } else {
;             const int kh = unit - qhi, b = row >> 12, t = row & 4095;
;             u16* kb = ea.kp + ((size_t)((b * ea.nh + kh) * 128 + (t >> 5)) * 4) * 512 + ((fq >> 1) * 32 + (t & 31)) * 8 + (fq & 1) * 4;
; #pragma unroll
;             for (int bj = 0; bj < 2; ++bj)
; #pragma unroll
.LBB0_603:
	s_andn2_b64 vcc, exec, s[36:37]
	s_cbranch_vccnz .LBB0_605
	v_mov_b64_e32 v[200:201], s[42:43]
	v_mad_i64_i32 v[200:201], s[14:15], v167, s45, v[200:201]
	v_lshl_add_u64 v[200:201], v[178:179], 1, v[200:201]
	v_cvt_pk_bf16_f32 v48, v182, v185
	v_cvt_pk_bf16_f32 v49, v208, v209
	v_cvt_pk_bf16_f32 v50, v211, v204
	v_cvt_pk_bf16_f32 v51, v136, v137
	v_cvt_pk_bf16_f32 v52, v171, v173
	v_cvt_pk_bf16_f32 v53, v175, v177
	v_cvt_pk_bf16_f32 v54, v135, v134
	v_cvt_pk_bf16_f32 v55, v131, v130
	v_mbcnt_lo_u32_b32 v56, -1, 0
	v_mbcnt_hi_u32_b32 v56, -1, v56
	v_and_b32_e32 v56, 16, v56
	v_lshrrev_b32_e32 v57, 1, v56
	v_add_u32_e32 v56, v56, v57
	v_mov_b32_e32 v57, 0
	v_permlane16_swap_b32_e32 v48, v50
	v_permlane16_swap_b32_e32 v49, v51
	v_permlane16_swap_b32_e32 v52, v54
	v_permlane16_swap_b32_e32 v53, v55
	v_lshl_add_u64 v[200:201], v[200:201], 0, v[56:57]
	global_store_dwordx4 v[200:201], v[48:51], off
	global_store_dwordx4 v[200:201], v[52:55], off offset:64
.LBB0_605:
	v_pk_mul_f32 v[132:133], v[44:45], v[158:159] op_sel_hi:[1,0]
	v_pk_mul_f32 v[200:201], v[40:41], v[158:159] op_sel_hi:[1,0]
	v_mul_f32_e32 v134, v133, v133
	v_mul_f32_e32 v135, v201, v201
	v_pk_mul_f32 v[130:131], v[46:47], v[158:159] op_sel_hi:[1,0]
	v_fmac_f32_e32 v134, v132, v132
	v_pk_mul_f32 v[136:137], v[42:43], v[158:159] op_sel_hi:[1,0]
	v_fmac_f32_e32 v135, v200, v200
	v_fmac_f32_e32 v134, v130, v130
	v_fmac_f32_e32 v135, v136, v136
	v_fmac_f32_e32 v134, v131, v131
	v_fmac_f32_e32 v135, v137, v137
	v_pk_mul_f32 v[206:207], v[36:37], v[158:159] op_sel_hi:[1,0]
	v_add_f32_e32 v134, v134, v135
	v_mul_f32_e32 v135, v207, v207
	v_pk_mul_f32 v[202:203], v[38:39], v[158:159] op_sel_hi:[1,0]
	v_fmac_f32_e32 v135, v206, v206
	v_fmac_f32_e32 v135, v202, v202
	v_fmac_f32_e32 v135, v203, v203
	v_pk_mul_f32 v[210:211], v[32:33], v[158:159] op_sel_hi:[1,0]
	v_add_f32_e32 v134, v135, v134
	v_mul_f32_e32 v135, v211, v211
	v_pk_mul_f32 v[208:209], v[34:35], v[158:159] op_sel_hi:[1,0]
	v_fmac_f32_e32 v135, v210, v210
	v_fmac_f32_e32 v135, v208, v208
	v_fmac_f32_e32 v135, v209, v209
	v_add_f32_e32 v134, v135, v134
	v_mov_b32_e32 v135, v134
	s_nop 1
	v_permlane16_swap_b32_e32 v134, v135
	v_add_f32_e32 v134, v134, v135
	v_mov_b32_e32 v135, v134
	s_nop 1
	v_permlane32_swap_b32_e32 v134, v135
	v_add_f32_e32 v134, v134, v135
	v_fmamk_f32 v134, v134, 0x3c800000, v218
	v_cmp_gt_f32_e32 vcc, s26, v134
	v_mul_f32_e32 v135, 0x4b800000, v134
	s_mov_b64 s[36:37], -1
	v_cndmask_b32_e32 v134, v134, v135, vcc
	v_rsq_f32_e32 v134, v134
	s_nop 0
	v_mul_f32_e32 v135, 0x45800000, v134
	v_cndmask_b32_e32 v182, v134, v135, vcc
	v_pk_mul_f32 v[132:133], v[132:133], v[182:183] op_sel_hi:[1,0]
	v_pk_mul_f32 v[136:137], v[136:137], v[182:183] op_sel_hi:[1,0]
	v_pk_mul_f32 v[134:135], v[186:187], v[132:133]
	v_pk_mul_f32 v[132:133], v[200:201], v[182:183] op_sel_hi:[1,0]
	v_pk_mul_f32 v[200:201], v[188:189], v[136:137]
	v_pk_mul_f32 v[136:137], v[206:207], v[182:183] op_sel_hi:[1,0]
	v_pk_mul_f32 v[206:207], v[210:211], v[182:183] op_sel_hi:[1,0]
	v_and_b32_e32 v210, 0xfdf, v165
	v_pk_mul_f32 v[204:205], v[190:191], v[132:133]
	v_pk_mul_f32 v[132:133], v[202:203], v[182:183] op_sel_hi:[1,0]
	v_pk_mul_f32 v[202:203], v[208:209], v[182:183] op_sel_hi:[1,0]
	v_lshlrev_b32_e32 v208, 8, v210
	v_mov_b32_e32 v209, v112
	v_lshl_add_u64 v[216:217], v[144:145], 0, v[208:209]
	global_load_dwordx4 v[212:215], v[216:217], off offset:16
	global_load_dwordx4 v[236:239], v[216:217], off
	v_pk_mul_f32 v[136:137], v[194:195], v[136:137]
	v_pk_mul_f32 v[130:131], v[130:131], v[182:183] op_sel_hi:[1,0]
	v_pk_mul_f32 v[132:133], v[192:193], v[132:133]
	v_pk_mul_f32 v[130:131], v[180:181], v[130:131]
	v_pk_mul_f32 v[206:207], v[198:199], v[206:207]
	v_pk_mul_f32 v[202:203], v[196:197], v[202:203]
	s_and_b64 vcc, exec, s[0:1]
	s_waitcnt vmcnt(0)
	v_mul_f32_e32 v175, v213, v130
	v_mul_f32_e32 v171, v237, v136
	v_fma_f32 v182, v236, v134, -v171
	v_mul_f32_e32 v171, v237, v134
	v_mul_f32_e32 v134, v239, v137
	v_fma_f32 v185, v238, v135, -v134
	v_mul_f32_e32 v134, v213, v132
	v_mul_f32_e32 v173, v239, v135
	v_fma_f32 v208, v212, v130, -v134
	v_mul_f32_e32 v130, v215, v133
	v_mul_f32_e32 v177, v215, v131
	v_fmac_f32_e32 v171, v236, v136
	v_fmac_f32_e32 v173, v238, v137
	v_fmac_f32_e32 v175, v212, v132
	v_fma_f32 v209, v214, v131, -v130
	v_fmac_f32_e32 v177, v214, v133
	global_load_dwordx4 v[130:133], v[216:217], off offset:144
	global_load_dwordx4 v[134:137], v[216:217], off offset:128
	s_waitcnt vmcnt(0)
	v_mul_f32_e32 v211, v135, v206
	v_mul_f32_e32 v135, v135, v204
	v_fma_f32 v211, v134, v204, -v211
	v_fmac_f32_e32 v135, v134, v206
	v_mul_f32_e32 v134, v137, v207
	v_fma_f32 v204, v136, v205, -v134
	v_mul_f32_e32 v134, v137, v205
	v_fmac_f32_e32 v134, v136, v207
	v_mul_f32_e32 v136, v131, v202
	v_mul_f32_e32 v131, v131, v200
	v_fma_f32 v136, v130, v200, -v136
	v_fmac_f32_e32 v131, v130, v202
	v_mul_f32_e32 v130, v133, v203
	v_fma_f32 v137, v132, v201, -v130
	v_mul_f32_e32 v130, v133, v201
	v_fmac_f32_e32 v130, v132, v203
	s_cbranch_vccnz .LBB0_607
	s_lshl_b32 s2, s76, 7
	v_lshl_add_u32 v132, v169, 8, s2
	v_lshrrev_b32_e32 v133, 5, v210
	v_or_b32_e32 v132, v132, v133
	v_ashrrev_i32_e32 v133, 31, v132
	v_lshlrev_b64 v[132:133], 12, v[132:133]
	v_lshl_add_u64 v[132:133], v[148:149], 0, v[132:133]
	s_mov_b64 s[36:37], 0
	v_cvt_pk_bf16_f32 v32, v182, v185
	v_cvt_pk_bf16_f32 v33, v208, v209
	v_cvt_pk_bf16_f32 v34, v211, v204
	v_cvt_pk_bf16_f32 v35, v136, v137
	v_cvt_pk_bf16_f32 v36, v171, v173
	v_cvt_pk_bf16_f32 v37, v175, v177
	v_cvt_pk_bf16_f32 v38, v135, v134
	v_cvt_pk_bf16_f32 v39, v131, v130
	v_mbcnt_lo_u32_b32 v40, -1, 0
	v_mbcnt_hi_u32_b32 v40, -1, v40
	v_and_b32_e32 v40, 16, v40
	v_mul_u32_u24_e32 v41, 63, v40
	v_lshrrev_b32_e32 v40, 1, v40
	v_add_u32_e32 v40, v40, v41
	v_mov_b32_e32 v41, 0
	v_permlane16_swap_b32_e32 v32, v34
	v_permlane16_swap_b32_e32 v33, v35
	v_permlane16_swap_b32_e32 v36, v38
	v_permlane16_swap_b32_e32 v37, v39
	v_lshl_add_u64 v[132:133], v[132:133], 0, v[40:41]
	global_store_dwordx4 v[132:133], v[32:35], off
	global_store_dwordx4 v[132:133], v[36:39], off offset:2048
; template <int EPI>
; __device__ __forceinline__ void gemm_epilogue(const f32x4 (&acc)[2][2][4][2], const Unit& u, int wr, int wc, int fr, int fq,
;                                               const EpiArgs& ea, const float (&rs_pre)[2][4]) {
;     ...
;         for (int m = 0; m < 4; ++m) {
;           const int row = row0 + ai * 128 + m * 16;
;           const float rs = rsr[ai][m];
;           f32x4 v[2][2];
;           float sq = 0.f;
; #pragma unroll
;           for (int bj = 0; bj < 2; ++bj)
; #pragma unroll
;             for (int n = 0; n < 2; ++n) {
;               v[bj][n] = acc[ai][bj][m][n] * rs;
;               sq += v[bj][n][0] * v[bj][n][0] + v[bj][n][1] * v[bj][n][1] + v[bj][n][2] * v[bj][n][2] + v[bj][n][3] * v[bj][n][3];
;             }
;           sq = xsum32(xsum16(sq));
;           const float hr = rsqrtf(sq * (1.f / 64.f) + EPS);
; #pragma unroll
;           for (int bj = 0; bj < 2; ++bj)
; #pragma unroll
;             for (int n = 0; n < 2; ++n) v[bj][n] = v[bj][n] * hr * gv[bj][n];
;           if constexpr (EPI == EPI_ODD) {
;             const int pos = row & 4095;
;             const float2* rope = reinterpret_cast<const float2*>(ea.aux_f2) + pos * 32 + 4 * fq;
; #pragma unroll
;             for (int n = 0; n < 2; ++n) {
;               f32x4 c01 = *reinterpret_cast<const f32x4*>(rope + n * 16);
;               f32x4 c23 = *reinterpret_cast<const f32x4*>(rope + n * 16 + 2);
;               float cs[4] = {c01[0], c01[2], c23[0], c23[2]}, sn[4] = {c01[1], c01[3], c23[1], c23[3]};
;               f32x4 x1 = v[0][n], x2 = v[1][n];
; #pragma unroll
;               for (int i = 0; i < 4; ++i) {
;                 v[0][n][i] = x1[i] * cs[i] - x2[i] * sn[i];
;                 v[1][n][i] = x2[i] * cs[i] + x1[i] * sn[i];
;               }
;             }
;           }
;           if (isq) {
; #pragma unroll
;             for (int bj = 0; bj < 2; ++bj)
; #pragma unroll
;               for (int n = 0; n < 2; ++n)
;                 *reinterpret_cast<uint2*>(ea.out_bf + (size_t)row * LD + lc0 + bj * 32 + n * 16) = pack4(v[bj][n]);
;           } else {
;             const int kh = unit - qhi, b = row >> 12, t = row & 4095;
;             u16* kb = ea.kp + ((size_t)((b * ea.nh + kh) * 128 + (t >> 5)) * 4) * 512 + ((fq >> 1) * 32 + (t & 31)) * 8 + (fq & 1) * 4;
; #pragma unroll
;             for (int bj = 0; bj < 2; ++bj)
; #pragma unroll
.LBB0_607:
	s_andn2_b64 vcc, exec, s[36:37]
	s_cbranch_vccnz .LBB0_609
	v_mov_b64_e32 v[200:201], s[42:43]
	v_mad_i64_i32 v[200:201], s[14:15], v165, s45, v[200:201]
	v_lshl_add_u64 v[200:201], v[178:179], 1, v[200:201]
	v_cvt_pk_bf16_f32 v32, v182, v185
	v_cvt_pk_bf16_f32 v33, v208, v209
	v_cvt_pk_bf16_f32 v34, v211, v204
	v_cvt_pk_bf16_f32 v35, v136, v137
	v_cvt_pk_bf16_f32 v36, v171, v173
	v_cvt_pk_bf16_f32 v37, v175, v177
	v_cvt_pk_bf16_f32 v38, v135, v134
	v_cvt_pk_bf16_f32 v39, v131, v130
	v_mbcnt_lo_u32_b32 v40, -1, 0
	v_mbcnt_hi_u32_b32 v40, -1, v40
	v_and_b32_e32 v40, 16, v40
	v_lshrrev_b32_e32 v41, 1, v40
	v_add_u32_e32 v40, v40, v41
	v_mov_b32_e32 v41, 0
	v_permlane16_swap_b32_e32 v32, v34
	v_permlane16_swap_b32_e32 v33, v35
	v_permlane16_swap_b32_e32 v36, v38
	v_permlane16_swap_b32_e32 v37, v39
	v_lshl_add_u64 v[200:201], v[200:201], 0, v[40:41]
	global_store_dwordx4 v[200:201], v[32:35], off
	global_store_dwordx4 v[200:201], v[36:39], off offset:64
.LBB0_609:
	v_pk_mul_f32 v[132:133], v[28:29], v[156:157] op_sel_hi:[1,0]
	v_pk_mul_f32 v[200:201], v[24:25], v[156:157] op_sel_hi:[1,0]
	v_mul_f32_e32 v134, v133, v133
	v_mul_f32_e32 v135, v201, v201
	v_pk_mul_f32 v[130:131], v[30:31], v[156:157] op_sel_hi:[1,0]
	v_fmac_f32_e32 v134, v132, v132
	v_pk_mul_f32 v[136:137], v[26:27], v[156:157] op_sel_hi:[1,0]
	v_fmac_f32_e32 v135, v200, v200
	v_fmac_f32_e32 v134, v130, v130
	v_fmac_f32_e32 v135, v136, v136
	v_fmac_f32_e32 v134, v131, v131
	v_fmac_f32_e32 v135, v137, v137
	v_pk_mul_f32 v[206:207], v[20:21], v[156:157] op_sel_hi:[1,0]
	v_add_f32_e32 v134, v134, v135
	v_mul_f32_e32 v135, v207, v207
	v_pk_mul_f32 v[202:203], v[22:23], v[156:157] op_sel_hi:[1,0]
	v_fmac_f32_e32 v135, v206, v206
	v_fmac_f32_e32 v135, v202, v202
	v_fmac_f32_e32 v135, v203, v203
	v_pk_mul_f32 v[210:211], v[16:17], v[156:157] op_sel_hi:[1,0]
	v_add_f32_e32 v134, v135, v134
	v_mul_f32_e32 v135, v211, v211
	v_pk_mul_f32 v[208:209], v[18:19], v[156:157] op_sel_hi:[1,0]
	v_fmac_f32_e32 v135, v210, v210
	v_fmac_f32_e32 v135, v208, v208
	v_fmac_f32_e32 v135, v209, v209
	v_add_f32_e32 v134, v135, v134
	v_mov_b32_e32 v135, v134
	s_nop 1
	v_permlane16_swap_b32_e32 v134, v135
	v_add_f32_e32 v134, v134, v135
	v_mov_b32_e32 v135, v134
	s_nop 1
	v_permlane32_swap_b32_e32 v134, v135
	v_add_f32_e32 v134, v134, v135
	v_fmamk_f32 v134, v134, 0x3c800000, v218
	v_cmp_gt_f32_e32 vcc, s26, v134
	v_mul_f32_e32 v135, 0x4b800000, v134
	s_mov_b64 s[36:37], -1
	v_cndmask_b32_e32 v134, v134, v135, vcc
	v_rsq_f32_e32 v134, v134
	s_nop 0
	v_mul_f32_e32 v135, 0x45800000, v134
	v_cndmask_b32_e32 v182, v134, v135, vcc
	v_pk_mul_f32 v[132:133], v[132:133], v[182:183] op_sel_hi:[1,0]
	v_pk_mul_f32 v[136:137], v[136:137], v[182:183] op_sel_hi:[1,0]
	v_pk_mul_f32 v[134:135], v[186:187], v[132:133]
	v_pk_mul_f32 v[132:133], v[200:201], v[182:183] op_sel_hi:[1,0]
	v_pk_mul_f32 v[200:201], v[188:189], v[136:137]
	v_pk_mul_f32 v[136:137], v[206:207], v[182:183] op_sel_hi:[1,0]
	v_pk_mul_f32 v[206:207], v[210:211], v[182:183] op_sel_hi:[1,0]
	v_and_b32_e32 v210, 0xfef, v163
	v_pk_mul_f32 v[204:205], v[190:191], v[132:133]
	v_pk_mul_f32 v[132:133], v[202:203], v[182:183] op_sel_hi:[1,0]
	v_pk_mul_f32 v[202:203], v[208:209], v[182:183] op_sel_hi:[1,0]
	v_lshlrev_b32_e32 v208, 8, v210
	v_mov_b32_e32 v209, v112
	v_lshl_add_u64 v[216:217], v[144:145], 0, v[208:209]
	global_load_dwordx4 v[212:215], v[216:217], off offset:16
	global_load_dwordx4 v[236:239], v[216:217], off
	v_pk_mul_f32 v[136:137], v[194:195], v[136:137]
	v_pk_mul_f32 v[130:131], v[130:131], v[182:183] op_sel_hi:[1,0]
	v_pk_mul_f32 v[132:133], v[192:193], v[132:133]
	v_pk_mul_f32 v[130:131], v[180:181], v[130:131]
	v_pk_mul_f32 v[206:207], v[198:199], v[206:207]
	v_pk_mul_f32 v[202:203], v[196:197], v[202:203]
	s_and_b64 vcc, exec, s[0:1]
	s_waitcnt vmcnt(0)
	v_mul_f32_e32 v175, v213, v130
	v_mul_f32_e32 v171, v237, v136
	v_fma_f32 v182, v236, v134, -v171
	v_mul_f32_e32 v171, v237, v134
	v_mul_f32_e32 v134, v239, v137
	v_fma_f32 v185, v238, v135, -v134
	v_mul_f32_e32 v134, v213, v132
	v_mul_f32_e32 v173, v239, v135
	v_fma_f32 v208, v212, v130, -v134
	v_mul_f32_e32 v130, v215, v133
	v_mul_f32_e32 v177, v215, v131
	v_fmac_f32_e32 v171, v236, v136
	v_fmac_f32_e32 v173, v238, v137
	v_fmac_f32_e32 v175, v212, v132
	v_fma_f32 v209, v214, v131, -v130
	v_fmac_f32_e32 v177, v214, v133
	global_load_dwordx4 v[130:133], v[216:217], off offset:144
	global_load_dwordx4 v[134:137], v[216:217], off offset:128
	s_waitcnt vmcnt(0)
	v_mul_f32_e32 v211, v135, v206
	v_mul_f32_e32 v135, v135, v204
	v_fma_f32 v211, v134, v204, -v211
	v_fmac_f32_e32 v135, v134, v206
	v_mul_f32_e32 v134, v137, v207
	v_fma_f32 v204, v136, v205, -v134
	v_mul_f32_e32 v134, v137, v205
	v_fmac_f32_e32 v134, v136, v207
	v_mul_f32_e32 v136, v131, v202
	v_mul_f32_e32 v131, v131, v200
	v_fma_f32 v136, v130, v200, -v136
	v_fmac_f32_e32 v131, v130, v202
	v_mul_f32_e32 v130, v133, v203
	v_fma_f32 v137, v132, v201, -v130
	v_mul_f32_e32 v130, v133, v201
	v_fmac_f32_e32 v130, v132, v203
	s_cbranch_vccnz .LBB0_611
	s_lshl_b32 s2, s76, 7
	v_lshl_add_u32 v132, v169, 8, s2
	v_lshrrev_b32_e32 v133, 5, v210
	v_or_b32_e32 v132, v132, v133
	v_ashrrev_i32_e32 v133, 31, v132
	v_lshlrev_b64 v[132:133], 12, v[132:133]
	v_lshl_add_u64 v[132:133], v[146:147], 0, v[132:133]
	s_mov_b64 s[36:37], 0
	v_cvt_pk_bf16_f32 v16, v182, v185
	v_cvt_pk_bf16_f32 v17, v208, v209
	v_cvt_pk_bf16_f32 v18, v211, v204
	v_cvt_pk_bf16_f32 v19, v136, v137
	v_cvt_pk_bf16_f32 v20, v171, v173
	v_cvt_pk_bf16_f32 v21, v175, v177
	v_cvt_pk_bf16_f32 v22, v135, v134
	v_cvt_pk_bf16_f32 v23, v131, v130
	v_mbcnt_lo_u32_b32 v24, -1, 0
	v_mbcnt_hi_u32_b32 v24, -1, v24
	v_and_b32_e32 v24, 16, v24
	v_mul_u32_u24_e32 v25, 63, v24
	v_lshrrev_b32_e32 v24, 1, v24
	v_add_u32_e32 v24, v24, v25
	v_mov_b32_e32 v25, 0
	v_permlane16_swap_b32_e32 v16, v18
	v_permlane16_swap_b32_e32 v17, v19
	v_permlane16_swap_b32_e32 v20, v22
	v_permlane16_swap_b32_e32 v21, v23
	v_lshl_add_u64 v[132:133], v[132:133], 0, v[24:25]
	global_store_dwordx4 v[132:133], v[16:19], off
	global_store_dwordx4 v[132:133], v[20:23], off offset:2048
; template <int EPI>
; __device__ __forceinline__ void gemm_epilogue(const f32x4 (&acc)[2][2][4][2], const Unit& u, int wr, int wc, int fr, int fq,
;                                               const EpiArgs& ea, const float (&rs_pre)[2][4]) {
;     ...
;         for (int m = 0; m < 4; ++m) {
;           const int row = row0 + ai * 128 + m * 16;
;           const float rs = rsr[ai][m];
;           f32x4 v[2][2];
;           float sq = 0.f;
; #pragma unroll
;           for (int bj = 0; bj < 2; ++bj)
; #pragma unroll
;             for (int n = 0; n < 2; ++n) {
;               v[bj][n] = acc[ai][bj][m][n] * rs;
;               sq += v[bj][n][0] * v[bj][n][0] + v[bj][n][1] * v[bj][n][1] + v[bj][n][2] * v[bj][n][2] + v[bj][n][3] * v[bj][n][3];
;             }
;           sq = xsum32(xsum16(sq));
;           const float hr = rsqrtf(sq * (1.f / 64.f) + EPS);
; #pragma unroll
;           for (int bj = 0; bj < 2; ++bj)
; #pragma unroll
;             for (int n = 0; n < 2; ++n) v[bj][n] = v[bj][n] * hr * gv[bj][n];
;           if constexpr (EPI == EPI_ODD) {
;             const int pos = row & 4095;
;             const float2* rope = reinterpret_cast<const float2*>(ea.aux_f2) + pos * 32 + 4 * fq;
; #pragma unroll
;             for (int n = 0; n < 2; ++n) {
;               f32x4 c01 = *reinterpret_cast<const f32x4*>(rope + n * 16);
;               f32x4 c23 = *reinterpret_cast<const f32x4*>(rope + n * 16 + 2);
;               float cs[4] = {c01[0], c01[2], c23[0], c23[2]}, sn[4] = {c01[1], c01[3], c23[1], c23[3]};
;               f32x4 x1 = v[0][n], x2 = v[1][n];
; #pragma unroll
;               for (int i = 0; i < 4; ++i) {
;                 v[0][n][i] = x1[i] * cs[i] - x2[i] * sn[i];
;                 v[1][n][i] = x2[i] * cs[i] + x1[i] * sn[i];
;               }
;             }
;           }
;           if (isq) {
; #pragma unroll
;             for (int bj = 0; bj < 2; ++bj)
; #pragma unroll
;               for (int n = 0; n < 2; ++n)
;                 *reinterpret_cast<uint2*>(ea.out_bf + (size_t)row * LD + lc0 + bj * 32 + n * 16) = pack4(v[bj][n]);
;           } else {
;             const int kh = unit - qhi, b = row >> 12, t = row & 4095;
;             u16* kb = ea.kp + ((size_t)((b * ea.nh + kh) * 128 + (t >> 5)) * 4) * 512 + ((fq >> 1) * 32 + (t & 31)) * 8 + (fq & 1) * 4;
; #pragma unroll
;             for (int bj = 0; bj < 2; ++bj)
; #pragma unroll
.LBB0_611:
	s_andn2_b64 vcc, exec, s[36:37]
	s_cbranch_vccnz .LBB0_613
	v_mov_b64_e32 v[200:201], s[42:43]
	v_mad_i64_i32 v[200:201], s[14:15], v163, s45, v[200:201]
	v_lshl_add_u64 v[200:201], v[178:179], 1, v[200:201]
	v_cvt_pk_bf16_f32 v16, v182, v185
	v_cvt_pk_bf16_f32 v17, v208, v209
	v_cvt_pk_bf16_f32 v18, v211, v204
	v_cvt_pk_bf16_f32 v19, v136, v137
	v_cvt_pk_bf16_f32 v20, v171, v173
	v_cvt_pk_bf16_f32 v21, v175, v177
	v_cvt_pk_bf16_f32 v22, v135, v134
	v_cvt_pk_bf16_f32 v23, v131, v130
	v_mbcnt_lo_u32_b32 v24, -1, 0
	v_mbcnt_hi_u32_b32 v24, -1, v24
	v_and_b32_e32 v24, 16, v24
	v_lshrrev_b32_e32 v25, 1, v24
	v_add_u32_e32 v24, v24, v25
	v_mov_b32_e32 v25, 0
	v_permlane16_swap_b32_e32 v16, v18
	v_permlane16_swap_b32_e32 v17, v19
	v_permlane16_swap_b32_e32 v20, v22
	v_permlane16_swap_b32_e32 v21, v23
	v_lshl_add_u64 v[200:201], v[200:201], 0, v[24:25]
	global_store_dwordx4 v[200:201], v[16:19], off
	global_store_dwordx4 v[200:201], v[20:23], off offset:64
.LBB0_613:
	v_pk_mul_f32 v[132:133], v[12:13], v[154:155] op_sel_hi:[1,0]
	v_pk_mul_f32 v[200:201], v[8:9], v[154:155] op_sel_hi:[1,0]
	v_mul_f32_e32 v134, v133, v133
	v_mul_f32_e32 v135, v201, v201
	v_pk_mul_f32 v[130:131], v[14:15], v[154:155] op_sel_hi:[1,0]
	v_fmac_f32_e32 v134, v132, v132
	v_pk_mul_f32 v[136:137], v[10:11], v[154:155] op_sel_hi:[1,0]
	v_fmac_f32_e32 v135, v200, v200
	v_fmac_f32_e32 v134, v130, v130
	v_fmac_f32_e32 v135, v136, v136
	v_fmac_f32_e32 v134, v131, v131
	v_fmac_f32_e32 v135, v137, v137
	v_pk_mul_f32 v[204:205], v[4:5], v[154:155] op_sel_hi:[1,0]
	v_add_f32_e32 v134, v134, v135
	v_mul_f32_e32 v135, v205, v205
	v_pk_mul_f32 v[202:203], v[6:7], v[154:155] op_sel_hi:[1,0]
	v_fmac_f32_e32 v135, v204, v204
	v_fmac_f32_e32 v135, v202, v202
	v_fmac_f32_e32 v135, v203, v203
	v_pk_mul_f32 v[208:209], v[0:1], v[154:155] op_sel_hi:[1,0]
	v_add_f32_e32 v134, v135, v134
	v_mul_f32_e32 v135, v209, v209
	v_pk_mul_f32 v[206:207], v[2:3], v[154:155] op_sel_hi:[1,0]
	v_fmac_f32_e32 v135, v208, v208
	v_fmac_f32_e32 v135, v206, v206
	v_fmac_f32_e32 v135, v207, v207
	v_add_f32_e32 v134, v135, v134
	v_mov_b32_e32 v135, v134
	s_nop 1
	v_permlane16_swap_b32_e32 v134, v135
	v_add_f32_e32 v134, v134, v135
	v_mov_b32_e32 v135, v134
	s_nop 1
	v_permlane32_swap_b32_e32 v134, v135
	v_add_f32_e32 v134, v134, v135
	v_fmamk_f32 v134, v134, 0x3c800000, v218
	v_cmp_gt_f32_e32 vcc, s26, v134
	v_mul_f32_e32 v135, 0x4b800000, v134
	s_mov_b64 s[36:37], -1
	v_cndmask_b32_e32 v134, v134, v135, vcc
	v_rsq_f32_e32 v134, v134
	s_nop 0
	v_mul_f32_e32 v135, 0x45800000, v134
	v_cndmask_b32_e32 v182, v134, v135, vcc
	v_pk_mul_f32 v[132:133], v[132:133], v[182:183] op_sel_hi:[1,0]
	v_pk_mul_f32 v[130:131], v[130:131], v[182:183] op_sel_hi:[1,0]
	v_pk_mul_f32 v[136:137], v[136:137], v[182:183] op_sel_hi:[1,0]
	v_pk_mul_f32 v[130:131], v[180:181], v[130:131]
	v_pk_mul_f32 v[134:135], v[186:187], v[132:133]
	v_pk_mul_f32 v[132:133], v[200:201], v[182:183] op_sel_hi:[1,0]
	v_pk_mul_f32 v[180:181], v[188:189], v[136:137]
	v_pk_mul_f32 v[136:137], v[204:205], v[182:183] op_sel_hi:[1,0]
	v_pk_mul_f32 v[188:189], v[190:191], v[132:133]
	v_pk_mul_f32 v[132:133], v[202:203], v[182:183] op_sel_hi:[1,0]
	v_pk_mul_f32 v[136:137], v[194:195], v[136:137]
	v_and_b32_e32 v194, 0xfff, v161
	v_pk_mul_f32 v[132:133], v[192:193], v[132:133]
	v_lshlrev_b32_e32 v192, 8, v194
	v_mov_b32_e32 v193, v112
	v_pk_mul_f32 v[190:191], v[208:209], v[182:183] op_sel_hi:[1,0]
	v_pk_mul_f32 v[186:187], v[206:207], v[182:183] op_sel_hi:[1,0]
	v_lshl_add_u64 v[204:205], v[144:145], 0, v[192:193]
	v_pk_mul_f32 v[186:187], v[196:197], v[186:187]
	v_pk_mul_f32 v[190:191], v[198:199], v[190:191]
	global_load_dwordx4 v[196:199], v[204:205], off offset:16
	global_load_dwordx4 v[200:203], v[204:205], off
	s_and_b64 vcc, exec, s[0:1]
	s_waitcnt vmcnt(0)
	v_mul_f32_e32 v175, v197, v130
	v_mul_f32_e32 v171, v201, v136
	v_fma_f32 v182, v200, v134, -v171
	v_mul_f32_e32 v171, v201, v134
	v_mul_f32_e32 v134, v203, v137
	v_fma_f32 v185, v202, v135, -v134
	v_mul_f32_e32 v134, v197, v132
	v_mul_f32_e32 v173, v203, v135
	v_fma_f32 v192, v196, v130, -v134
	v_mul_f32_e32 v130, v199, v133
	v_mul_f32_e32 v177, v199, v131
	v_fmac_f32_e32 v171, v200, v136
	v_fmac_f32_e32 v173, v202, v137
	v_fmac_f32_e32 v175, v196, v132
	v_fma_f32 v193, v198, v131, -v130
	v_fmac_f32_e32 v177, v198, v133
	global_load_dwordx4 v[130:133], v[204:205], off offset:144
	global_load_dwordx4 v[134:137], v[204:205], off offset:128
	s_waitcnt vmcnt(0)
	v_mul_f32_e32 v195, v135, v190
	v_mul_f32_e32 v135, v135, v188
	v_fma_f32 v195, v134, v188, -v195
	v_fmac_f32_e32 v135, v134, v190
	v_mul_f32_e32 v134, v137, v191
	v_fma_f32 v188, v136, v189, -v134
	v_mul_f32_e32 v134, v137, v189
	v_fmac_f32_e32 v134, v136, v191
	v_mul_f32_e32 v136, v131, v186
	v_mul_f32_e32 v131, v131, v180
	v_fma_f32 v136, v130, v180, -v136
	v_fmac_f32_e32 v131, v130, v186
	v_mul_f32_e32 v130, v133, v187
	v_fma_f32 v137, v132, v181, -v130
	v_mul_f32_e32 v130, v133, v181
	v_fmac_f32_e32 v130, v132, v187
	s_cbranch_vccnz .LBB0_615
	s_lshl_b32 s0, s76, 7
	v_lshl_add_u32 v132, v169, 8, s0
	v_lshrrev_b32_e32 v133, 5, v194
	v_or_b32_e32 v132, v132, v133
	v_ashrrev_i32_e32 v133, 31, v132
	v_lshlrev_b64 v[132:133], 12, v[132:133]
	v_lshl_add_u64 v[132:133], v[148:149], 0, v[132:133]
	s_mov_b64 s[36:37], 0
	v_cvt_pk_bf16_f32 v0, v182, v185
	v_cvt_pk_bf16_f32 v1, v192, v193
	v_cvt_pk_bf16_f32 v2, v195, v188
	v_cvt_pk_bf16_f32 v3, v136, v137
	v_cvt_pk_bf16_f32 v4, v171, v173
	v_cvt_pk_bf16_f32 v5, v175, v177
	v_cvt_pk_bf16_f32 v6, v135, v134
	v_cvt_pk_bf16_f32 v7, v131, v130
	v_mbcnt_lo_u32_b32 v8, -1, 0
	v_mbcnt_hi_u32_b32 v8, -1, v8
	v_and_b32_e32 v8, 16, v8
	v_mul_u32_u24_e32 v9, 63, v8
	v_lshrrev_b32_e32 v8, 1, v8
	v_add_u32_e32 v8, v8, v9
	v_mov_b32_e32 v9, 0
	v_permlane16_swap_b32_e32 v0, v2
	v_permlane16_swap_b32_e32 v1, v3
	v_permlane16_swap_b32_e32 v4, v6
	v_permlane16_swap_b32_e32 v5, v7
	v_lshl_add_u64 v[132:133], v[132:133], 0, v[8:9]
	global_store_dwordx4 v[132:133], v[0:3], off
	global_store_dwordx4 v[132:133], v[4:7], off offset:2048
.LBB0_615:
	s_andn2_b64 vcc, exec, s[36:37]
	s_cbranch_vccnz .LBB0_617
	v_mov_b64_e32 v[180:181], s[42:43]
	v_mad_i64_i32 v[180:181], s[0:1], v161, s45, v[180:181]
	v_lshl_add_u64 v[180:181], v[178:179], 1, v[180:181]
	v_cvt_pk_bf16_f32 v0, v182, v185
	v_cvt_pk_bf16_f32 v1, v192, v193
	v_cvt_pk_bf16_f32 v2, v195, v188
	v_cvt_pk_bf16_f32 v3, v136, v137
	v_cvt_pk_bf16_f32 v4, v171, v173
	v_cvt_pk_bf16_f32 v5, v175, v177
	v_cvt_pk_bf16_f32 v6, v135, v134
	v_cvt_pk_bf16_f32 v7, v131, v130
	v_mbcnt_lo_u32_b32 v8, -1, 0
	v_mbcnt_hi_u32_b32 v8, -1, v8
	v_and_b32_e32 v8, 16, v8
	v_lshrrev_b32_e32 v9, 1, v8
	v_add_u32_e32 v8, v8, v9
	v_mov_b32_e32 v9, 0
	v_permlane16_swap_b32_e32 v0, v2
	v_permlane16_swap_b32_e32 v1, v3
	v_permlane16_swap_b32_e32 v4, v6
	v_permlane16_swap_b32_e32 v5, v7
	v_lshl_add_u64 v[180:181], v[180:181], 0, v[8:9]
	global_store_dwordx4 v[180:181], v[0:3], off
	global_store_dwordx4 v[180:181], v[4:7], off offset:64
